# drop the redundant mid-block s_setprio 0/1 pairs inside each 32-MFMA block
# speedup vs baseline: 1.0148x; 1.0148x over previous
; #define PG8_STAGE(bufoff, gbase, voff) do { _Pragma("unroll") for (int _i = 0; _i < 2; ++_i) \
;         __builtin_amdgcn_global_load_lds((const unsigned*)((const char*)(gbase) + (voff)[_i]), (PG8_LAS unsigned*)(lds + (bufoff) + ldsw + _i * 8192), 16, 0, 0); } while (0)
; #define PG8_LDA(dst, b, h) do { _Pragma("unroll") for (int m = 0; m < 4; ++m) _Pragma("unroll") for (int k = 0; k < 2; ++k) dst[m][k] = *(const PG8_LAS bf16x8*)(lds + PG8_SA(b, h) + aoff + m * 2048 + k * 1024); } while (0)
; #define PG8_LDB(dst, b, h) do { _Pragma("unroll") for (int n = 0; n < 2; ++n) _Pragma("unroll") for (int k = 0; k < 2; ++k) dst[n][k] = *(const PG8_LAS bf16x8*)(lds + PG8_SB(b, h) + boff + n * 2048 + k * 1024); } while (0)
; #define PG8_MMA(ai, bj, At, Bt) do { __builtin_amdgcn_s_setprio(1); _Pragma("unroll") for (int m = 0; m < 4; ++m) _Pragma("unroll") for (int n = 0; n < 2; ++n) _Pragma("unroll") for (int k = 0; k < 2; ++k) \
;         acc[ai][bj][m][n] = __builtin_amdgcn_mfma_f32_16x16x32_bf16(Bt[n][k], At[m][k], acc[ai][bj][m][n], 0, 0, 0); __builtin_amdgcn_s_setprio(0); } while (0)
; #define PG8_WAIT_V(n) asm volatile("s_waitcnt vmcnt(" #n ")" ::: "memory")
; #define PG8_WAIT_L(n) asm volatile("s_waitcnt lgkmcnt(" #n ")" ::: "memory")
; #define PG8_BAR __builtin_amdgcn_s_barrier()
; #define PG8_SCHED __builtin_amdgcn_sched_barrier(0)
; template <class Epi, class Sched, bool ALIGN_EPI = false, bool SP2 = false>
; __device__ __forceinline__ void gemm_phase(PG8_LAS unsigned char* lds, const Gemm g, const Sched& S, const Epi& E) {
;     ...
;             PG8_LDB(B0, 0, 0); PG8_LDB(B1, 0, 1); PG8_SCHED; PG8_LDA(At, 0, 0); PG8_STAGE(PG8_SA(1, 1), a1 + hstep, voffA);
;             PG8_WAIT_V(8); PG8_WAIT_L(0); PG8_BAR; PG8_MMA(0, 0, At, B0); PG8_MMA(0, 1, At, B1); PG8_BAR; PG8_SCHED;
;             PG8_LDA(At, 0, 1); PG8_STAGE(PG8_SB(0, 0), b2, voffB); PG8_STAGE(PG8_SB(0, 1), b2 + hstep, voffB); PG8_STAGE(PG8_SA(0, 0), a2, voffA);
;             PG8_WAIT_V(8); PG8_WAIT_L(0); PG8_BAR; PG8_MMA(1, 0, At, B0); PG8_MMA(1, 1, At, B1); PG8_BAR; PG8_SCHED;
.LBB0_63:
	s_add_i32 s66, s46, 2
	s_add_u32 s10, s44, 0x80
	s_addc_u32 s11, s45, 0
	s_add_i32 s67, 0, 0x10000
	s_cmp_eq_u32 s74, s46
	s_cselect_b32 s47, s63, s11
	s_cselect_b32 s46, s62, s10
	s_cselect_b32 s79, s65, s20
	s_cselect_b32 s78, s64, s19
	s_add_i32 s10, 0, 0x14000
	v_add_u32_e32 v140, s67, v183
	v_add_u32_e32 v166, s10, v183
	ds_read_b128 v[128:131], v140
	ds_read_b128 v[132:135], v140 offset:1024
	ds_read_b128 v[136:139], v140 offset:2048
	ds_read_b128 v[140:143], v140 offset:3072
	ds_read_b128 v[144:147], v166
	ds_read_b128 v[148:151], v166 offset:1024
	ds_read_b128 v[152:155], v166 offset:2048
	ds_read_b128 v[166:169], v166 offset:3072
	v_lshl_add_u64 v[190:191], s[44:45], 0, v[162:163]
	s_add_i32 m0, s23, 0xc000
	ds_read_b128 v[170:173], v185
	ds_read_b128 v[174:177], v185 offset:1024
	ds_read_b128 v[178:181], v185 offset:2048
	ds_read_b128 v[186:189], v185 offset:3072
	ds_read_b128 v[194:197], v185 offset:4096
	ds_read_b128 v[198:201], v185 offset:5120
	ds_read_b128 v[202:205], v185 offset:6144
	ds_read_b128 v[206:209], v185 offset:7168
	global_load_lds_dwordx4 v[190:191], off
	v_lshl_add_u64 v[190:191], s[44:45], 0, v[164:165]
	s_add_i32 m0, s23, 0xe000
	s_nop 0
	global_load_lds_dwordx4 v[190:191], off
	s_waitcnt vmcnt(8)
	s_waitcnt lgkmcnt(0)
	s_barrier
	s_setprio 1
	s_waitcnt lgkmcnt(0)
	v_mfma_f32_16x16x32_bf16 v[124:127], v[128:131], v[170:173], v[124:127]
	v_mfma_f32_16x16x32_bf16 v[120:123], v[136:139], v[170:173], v[120:123]
	v_mfma_f32_16x16x32_bf16 v[108:111], v[128:131], v[178:181], v[108:111]
	v_mfma_f32_16x16x32_bf16 v[104:107], v[136:139], v[178:181], v[104:107]
	v_mfma_f32_16x16x32_bf16 v[92:95], v[128:131], v[194:197], v[92:95]
	v_mfma_f32_16x16x32_bf16 v[88:91], v[136:139], v[194:197], v[88:91]
	v_mfma_f32_16x16x32_bf16 v[76:79], v[128:131], v[202:205], v[76:79]
	v_mfma_f32_16x16x32_bf16 v[72:75], v[136:139], v[202:205], v[72:75]
	v_mfma_f32_16x16x32_bf16 v[124:127], v[132:135], v[174:177], v[124:127]
	v_mfma_f32_16x16x32_bf16 v[120:123], v[140:143], v[174:177], v[120:123]
	v_mfma_f32_16x16x32_bf16 v[108:111], v[132:135], v[186:189], v[108:111]
	v_mfma_f32_16x16x32_bf16 v[104:107], v[140:143], v[186:189], v[104:107]
	v_mfma_f32_16x16x32_bf16 v[92:95], v[132:135], v[198:201], v[92:95]
	v_mfma_f32_16x16x32_bf16 v[88:91], v[140:143], v[198:201], v[88:91]
	v_mfma_f32_16x16x32_bf16 v[76:79], v[132:135], v[206:209], v[76:79]
	v_mfma_f32_16x16x32_bf16 v[72:75], v[140:143], v[206:209], v[72:75]
	v_mfma_f32_16x16x32_bf16 v[116:119], v[144:147], v[170:173], v[116:119]
	v_mfma_f32_16x16x32_bf16 v[112:115], v[152:155], v[170:173], v[112:115]
	v_mfma_f32_16x16x32_bf16 v[100:103], v[144:147], v[178:181], v[100:103]
	v_mfma_f32_16x16x32_bf16 v[96:99], v[152:155], v[178:181], v[96:99]
	v_mfma_f32_16x16x32_bf16 v[84:87], v[144:147], v[194:197], v[84:87]
	v_mfma_f32_16x16x32_bf16 v[80:83], v[152:155], v[194:197], v[80:83]
	v_mfma_f32_16x16x32_bf16 v[68:71], v[144:147], v[202:205], v[68:71]
	v_mfma_f32_16x16x32_bf16 v[64:67], v[152:155], v[202:205], v[64:67]
	v_mfma_f32_16x16x32_bf16 v[116:119], v[148:151], v[174:177], v[116:119]
	v_mfma_f32_16x16x32_bf16 v[112:115], v[166:169], v[174:177], v[112:115]
	v_mfma_f32_16x16x32_bf16 v[100:103], v[148:151], v[186:189], v[100:103]
	v_mfma_f32_16x16x32_bf16 v[96:99], v[166:169], v[186:189], v[96:99]
	v_mfma_f32_16x16x32_bf16 v[84:87], v[148:151], v[198:201], v[84:87]
	v_mfma_f32_16x16x32_bf16 v[80:83], v[166:169], v[198:201], v[80:83]
	v_mfma_f32_16x16x32_bf16 v[68:71], v[148:151], v[206:209], v[68:71]
	v_mfma_f32_16x16x32_bf16 v[64:67], v[166:169], v[206:209], v[64:67]
	s_setprio 0
	s_barrier
	s_add_i32 s11, s67, s22
	v_lshl_add_u64 v[190:191], s[78:79], 0, v[192:193]
	s_mov_b32 m0, s11
	ds_read_b128 v[170:173], v185 offset:16384
	ds_read_b128 v[174:177], v185 offset:17408
	ds_read_b128 v[178:181], v185 offset:18432
	ds_read_b128 v[186:189], v185 offset:19456
	ds_read_b128 v[194:197], v185 offset:20480
	ds_read_b128 v[198:201], v185 offset:21504
	ds_read_b128 v[202:205], v185 offset:22528
	ds_read_b128 v[206:209], v185 offset:23552
	global_load_lds_dwordx4 v[190:191], off
	s_add_i32 m0, s11, 0x2000
	v_lshl_add_u64 v[210:211], s[78:79], 0, v[160:161]
	s_add_u32 s78, s78, s52
	s_addc_u32 s79, s79, 0
	s_add_i32 s10, s10, s22
	global_load_lds_dwordx4 v[210:211], off
	v_lshl_add_u64 v[212:213], s[78:79], 0, v[192:193]
	s_mov_b32 m0, s10
	v_lshl_add_u64 v[214:215], s[78:79], 0, v[160:161]
	global_load_lds_dwordx4 v[212:213], off
	s_add_i32 m0, s10, 0x2000
	v_lshl_add_u64 v[216:217], s[46:47], 0, v[156:157]
	global_load_lds_dwordx4 v[214:215], off
	s_mov_b32 m0, s23
	v_lshl_add_u64 v[218:219], s[46:47], 0, v[158:159]
	global_load_lds_dwordx4 v[216:217], off
	s_mov_b32 m0, s51
	s_nop 0
	global_load_lds_dwordx4 v[218:219], off
	s_waitcnt vmcnt(8)
	s_waitcnt lgkmcnt(0)
	s_barrier
; #define PG8_STAGE(bufoff, gbase, voff) do { _Pragma("unroll") for (int _i = 0; _i < 2; ++_i) \
;         __builtin_amdgcn_global_load_lds((const unsigned*)((const char*)(gbase) + (voff)[_i]), (PG8_LAS unsigned*)(lds + (bufoff) + ldsw + _i * 8192), 16, 0, 0); } while (0)
; #define PG8_LDA(dst, b, h) do { _Pragma("unroll") for (int m = 0; m < 4; ++m) _Pragma("unroll") for (int k = 0; k < 2; ++k) dst[m][k] = *(const PG8_LAS bf16x8*)(lds + PG8_SA(b, h) + aoff + m * 2048 + k * 1024); } while (0)
; #define PG8_LDB(dst, b, h) do { _Pragma("unroll") for (int n = 0; n < 2; ++n) _Pragma("unroll") for (int k = 0; k < 2; ++k) dst[n][k] = *(const PG8_LAS bf16x8*)(lds + PG8_SB(b, h) + boff + n * 2048 + k * 1024); } while (0)
; #define PG8_MMA(ai, bj, At, Bt) do { __builtin_amdgcn_s_setprio(1); _Pragma("unroll") for (int m = 0; m < 4; ++m) _Pragma("unroll") for (int n = 0; n < 2; ++n) _Pragma("unroll") for (int k = 0; k < 2; ++k) \
;         acc[ai][bj][m][n] = __builtin_amdgcn_mfma_f32_16x16x32_bf16(Bt[n][k], At[m][k], acc[ai][bj][m][n], 0, 0, 0); __builtin_amdgcn_s_setprio(0); } while (0)
; #define PG8_WAIT_V(n) asm volatile("s_waitcnt vmcnt(" #n ")" ::: "memory")
; #define PG8_WAIT_L(n) asm volatile("s_waitcnt lgkmcnt(" #n ")" ::: "memory")
; #define PG8_BAR __builtin_amdgcn_s_barrier()
; #define PG8_SCHED __builtin_amdgcn_sched_barrier(0)
; template <class Epi, class Sched, bool ALIGN_EPI = false, bool SP2 = false>
; __device__ __forceinline__ void gemm_phase(PG8_LAS unsigned char* lds, const Gemm g, const Sched& S, const Epi& E) {
;     ...
;             PG8_WAIT_V(8); PG8_WAIT_L(0); PG8_BAR; PG8_MMA(1, 0, At, B0); PG8_MMA(1, 1, At, B1); PG8_BAR; PG8_SCHED;
;             PG8_LDB(B0, 1, 0); PG8_LDB(B1, 1, 1); PG8_SCHED; PG8_LDA(At, 1, 0); PG8_STAGE(PG8_SA(0, 1), a2 + hstep, voffA);
;             PG8_WAIT_V(8); PG8_WAIT_L(0); PG8_BAR; PG8_MMA(0, 0, At, B0); PG8_MMA(0, 1, At, B1); PG8_BAR; PG8_SCHED;
	s_setprio 1
	s_waitcnt lgkmcnt(0)
	v_mfma_f32_16x16x32_bf16 v[60:63], v[128:131], v[170:173], v[60:63]
	v_mfma_f32_16x16x32_bf16 v[56:59], v[136:139], v[170:173], v[56:59]
	v_mfma_f32_16x16x32_bf16 v[44:47], v[128:131], v[178:181], v[44:47]
	v_mfma_f32_16x16x32_bf16 v[40:43], v[136:139], v[178:181], v[40:43]
	v_mfma_f32_16x16x32_bf16 v[28:31], v[128:131], v[194:197], v[28:31]
	v_mfma_f32_16x16x32_bf16 v[24:27], v[136:139], v[194:197], v[24:27]
	v_mfma_f32_16x16x32_bf16 v[12:15], v[128:131], v[202:205], v[12:15]
	v_mfma_f32_16x16x32_bf16 v[8:11], v[136:139], v[202:205], v[8:11]
	v_mfma_f32_16x16x32_bf16 v[60:63], v[132:135], v[174:177], v[60:63]
	v_mfma_f32_16x16x32_bf16 v[56:59], v[140:143], v[174:177], v[56:59]
	v_mfma_f32_16x16x32_bf16 v[44:47], v[132:135], v[186:189], v[44:47]
	v_mfma_f32_16x16x32_bf16 v[40:43], v[140:143], v[186:189], v[40:43]
	v_mfma_f32_16x16x32_bf16 v[28:31], v[132:135], v[198:201], v[28:31]
	v_mfma_f32_16x16x32_bf16 v[24:27], v[140:143], v[198:201], v[24:27]
	v_mfma_f32_16x16x32_bf16 v[12:15], v[132:135], v[206:209], v[12:15]
	v_mfma_f32_16x16x32_bf16 v[8:11], v[140:143], v[206:209], v[8:11]
	v_mfma_f32_16x16x32_bf16 v[52:55], v[144:147], v[170:173], v[52:55]
	v_mfma_f32_16x16x32_bf16 v[48:51], v[152:155], v[170:173], v[48:51]
	v_mfma_f32_16x16x32_bf16 v[36:39], v[144:147], v[178:181], v[36:39]
	v_mfma_f32_16x16x32_bf16 v[32:35], v[152:155], v[178:181], v[32:35]
	v_mfma_f32_16x16x32_bf16 v[20:23], v[144:147], v[194:197], v[20:23]
	v_mfma_f32_16x16x32_bf16 v[16:19], v[152:155], v[194:197], v[16:19]
	v_mfma_f32_16x16x32_bf16 v[4:7], v[144:147], v[202:205], v[4:7]
	v_mfma_f32_16x16x32_bf16 v[0:3], v[152:155], v[202:205], v[0:3]
	v_mfma_f32_16x16x32_bf16 v[52:55], v[148:151], v[174:177], v[52:55]
	v_mfma_f32_16x16x32_bf16 v[48:51], v[166:169], v[174:177], v[48:51]
	v_mfma_f32_16x16x32_bf16 v[36:39], v[148:151], v[186:189], v[36:39]
	v_mfma_f32_16x16x32_bf16 v[32:35], v[166:169], v[186:189], v[32:35]
	v_mfma_f32_16x16x32_bf16 v[20:23], v[148:151], v[198:201], v[20:23]
	v_mfma_f32_16x16x32_bf16 v[16:19], v[166:169], v[198:201], v[16:19]
	v_mfma_f32_16x16x32_bf16 v[4:7], v[148:151], v[206:209], v[4:7]
	v_mfma_f32_16x16x32_bf16 v[0:3], v[166:169], v[206:209], v[0:3]
	s_setprio 0
	s_barrier
	s_add_i32 s10, 0, 0x18000
	s_add_i32 s11, 0, 0x1c000
	v_add_u32_e32 v140, s10, v183
	v_add_u32_e32 v166, s11, v183
	ds_read_b128 v[128:131], v140
	ds_read_b128 v[132:135], v140 offset:1024
	ds_read_b128 v[136:139], v140 offset:2048
	ds_read_b128 v[140:143], v140 offset:3072
	ds_read_b128 v[144:147], v166
	ds_read_b128 v[148:151], v166 offset:1024
	ds_read_b128 v[152:155], v166 offset:2048
	ds_read_b128 v[166:169], v166 offset:3072
	s_add_u32 s46, s46, s52
	s_addc_u32 s47, s47, 0
	s_mov_b32 m0, s68
	v_lshl_add_u64 v[220:221], s[46:47], 0, v[156:157]
	ds_read_b128 v[170:173], v185 offset:32768
	ds_read_b128 v[174:177], v185 offset:33792
	ds_read_b128 v[178:181], v185 offset:34816
	ds_read_b128 v[186:189], v185 offset:35840
	ds_read_b128 v[194:197], v185 offset:36864
	ds_read_b128 v[198:201], v185 offset:37888
	ds_read_b128 v[202:205], v185 offset:38912
	ds_read_b128 v[206:209], v185 offset:39936
	global_load_lds_dwordx4 v[220:221], off
	v_lshl_add_u64 v[220:221], s[46:47], 0, v[158:159]
	s_mov_b32 m0, s69
	s_nop 0
	global_load_lds_dwordx4 v[220:221], off
	s_waitcnt vmcnt(8)
	s_waitcnt lgkmcnt(0)
	s_barrier
	s_setprio 1
	s_waitcnt lgkmcnt(0)
	v_mfma_f32_16x16x32_bf16 v[124:127], v[128:131], v[170:173], v[124:127]
	v_mfma_f32_16x16x32_bf16 v[120:123], v[136:139], v[170:173], v[120:123]
	v_mfma_f32_16x16x32_bf16 v[108:111], v[128:131], v[178:181], v[108:111]
	v_mfma_f32_16x16x32_bf16 v[104:107], v[136:139], v[178:181], v[104:107]
	v_mfma_f32_16x16x32_bf16 v[92:95], v[128:131], v[194:197], v[92:95]
	v_mfma_f32_16x16x32_bf16 v[88:91], v[136:139], v[194:197], v[88:91]
	v_mfma_f32_16x16x32_bf16 v[76:79], v[128:131], v[202:205], v[76:79]
	v_mfma_f32_16x16x32_bf16 v[72:75], v[136:139], v[202:205], v[72:75]
	v_mfma_f32_16x16x32_bf16 v[124:127], v[132:135], v[174:177], v[124:127]
	v_mfma_f32_16x16x32_bf16 v[120:123], v[140:143], v[174:177], v[120:123]
	v_mfma_f32_16x16x32_bf16 v[108:111], v[132:135], v[186:189], v[108:111]
	v_mfma_f32_16x16x32_bf16 v[104:107], v[140:143], v[186:189], v[104:107]
	v_mfma_f32_16x16x32_bf16 v[92:95], v[132:135], v[198:201], v[92:95]
	v_mfma_f32_16x16x32_bf16 v[88:91], v[140:143], v[198:201], v[88:91]
	v_mfma_f32_16x16x32_bf16 v[76:79], v[132:135], v[206:209], v[76:79]
	v_mfma_f32_16x16x32_bf16 v[72:75], v[140:143], v[206:209], v[72:75]
	v_mfma_f32_16x16x32_bf16 v[116:119], v[144:147], v[170:173], v[116:119]
	v_mfma_f32_16x16x32_bf16 v[112:115], v[152:155], v[170:173], v[112:115]
	v_mfma_f32_16x16x32_bf16 v[100:103], v[144:147], v[178:181], v[100:103]
	v_mfma_f32_16x16x32_bf16 v[96:99], v[152:155], v[178:181], v[96:99]
	v_mfma_f32_16x16x32_bf16 v[84:87], v[144:147], v[194:197], v[84:87]
	v_mfma_f32_16x16x32_bf16 v[80:83], v[152:155], v[194:197], v[80:83]
	v_mfma_f32_16x16x32_bf16 v[68:71], v[144:147], v[202:205], v[68:71]
	v_mfma_f32_16x16x32_bf16 v[64:67], v[152:155], v[202:205], v[64:67]
	v_mfma_f32_16x16x32_bf16 v[116:119], v[148:151], v[174:177], v[116:119]
	v_mfma_f32_16x16x32_bf16 v[112:115], v[166:169], v[174:177], v[112:115]
	v_mfma_f32_16x16x32_bf16 v[100:103], v[148:151], v[186:189], v[100:103]
	v_mfma_f32_16x16x32_bf16 v[96:99], v[166:169], v[186:189], v[96:99]
	v_mfma_f32_16x16x32_bf16 v[84:87], v[148:151], v[198:201], v[84:87]
	v_mfma_f32_16x16x32_bf16 v[80:83], v[166:169], v[198:201], v[80:83]
	v_mfma_f32_16x16x32_bf16 v[68:71], v[148:151], v[206:209], v[68:71]
	v_mfma_f32_16x16x32_bf16 v[64:67], v[166:169], v[206:209], v[64:67]
	s_setprio 0
	s_barrier
; #define PG8_STAGE(bufoff, gbase, voff) do { _Pragma("unroll") for (int _i = 0; _i < 2; ++_i) \
;         __builtin_amdgcn_global_load_lds((const unsigned*)((const char*)(gbase) + (voff)[_i]), (PG8_LAS unsigned*)(lds + (bufoff) + ldsw + _i * 8192), 16, 0, 0); } while (0)
; #define PG8_LDA(dst, b, h) do { _Pragma("unroll") for (int m = 0; m < 4; ++m) _Pragma("unroll") for (int k = 0; k < 2; ++k) dst[m][k] = *(const PG8_LAS bf16x8*)(lds + PG8_SA(b, h) + aoff + m * 2048 + k * 1024); } while (0)
; #define PG8_MMA(ai, bj, At, Bt) do { __builtin_amdgcn_s_setprio(1); _Pragma("unroll") for (int m = 0; m < 4; ++m) _Pragma("unroll") for (int n = 0; n < 2; ++n) _Pragma("unroll") for (int k = 0; k < 2; ++k) \
;         acc[ai][bj][m][n] = __builtin_amdgcn_mfma_f32_16x16x32_bf16(Bt[n][k], At[m][k], acc[ai][bj][m][n], 0, 0, 0); __builtin_amdgcn_s_setprio(0); } while (0)
; #define PG8_WAIT_V(n) asm volatile("s_waitcnt vmcnt(" #n ")" ::: "memory")
; #define PG8_WAIT_L(n) asm volatile("s_waitcnt lgkmcnt(" #n ")" ::: "memory")
; #define PG8_BAR __builtin_amdgcn_s_barrier()
; #define PG8_SCHED __builtin_amdgcn_sched_barrier(0)
; template <class Epi, class Sched, bool ALIGN_EPI = false, bool SP2 = false>
; __device__ __forceinline__ void gemm_phase(PG8_LAS unsigned char* lds, const Gemm g, const Sched& S, const Epi& E) {
;     ...
;             PG8_LDA(At, 1, 1); PG8_STAGE(PG8_SB(1, 0), b3, voffB); PG8_STAGE(PG8_SB(1, 1), b3 + hstep, voffB); PG8_STAGE(PG8_SA(1, 0), a3, voffA);
;             PG8_WAIT_V(8); PG8_WAIT_L(0); PG8_BAR; PG8_MMA(1, 0, At, B0); PG8_MMA(1, 1, At, B1); PG8_BAR; PG8_SCHED;
;     ...
;         if constexpr (ALIGN_EPI) { if (wr == 0) PG8_BAR; }
	s_add_i32 s10, s10, s22
	v_lshl_add_u64 v[190:191], v[190:191], 0, s[36:37]
	s_mov_b32 m0, s10
	ds_read_b128 v[170:173], v185 offset:49152
	ds_read_b128 v[174:177], v185 offset:50176
	ds_read_b128 v[178:181], v185 offset:51200
	ds_read_b128 v[186:189], v185 offset:52224
	ds_read_b128 v[194:197], v185 offset:53248
	ds_read_b128 v[198:201], v185 offset:54272
	ds_read_b128 v[202:205], v185 offset:55296
	ds_read_b128 v[206:209], v185 offset:56320
	global_load_lds_dwordx4 v[190:191], off
	v_lshl_add_u64 v[190:191], v[210:211], 0, s[36:37]
	s_add_i32 m0, s10, 0x2000
	s_add_i32 s10, s11, s22
	global_load_lds_dwordx4 v[190:191], off
	v_lshl_add_u64 v[190:191], v[212:213], 0, s[36:37]
	s_mov_b32 m0, s10
	s_nop 0
	global_load_lds_dwordx4 v[190:191], off
	v_lshl_add_u64 v[190:191], v[214:215], 0, s[36:37]
	s_add_i32 m0, s10, 0x2000
	s_nop 0
	global_load_lds_dwordx4 v[190:191], off
	v_lshl_add_u64 v[190:191], v[216:217], 0, s[36:37]
	s_mov_b32 m0, s70
	s_nop 0
	global_load_lds_dwordx4 v[190:191], off
	v_lshl_add_u64 v[190:191], v[218:219], 0, s[36:37]
	s_mov_b32 m0, s71
	s_nop 0
	global_load_lds_dwordx4 v[190:191], off
	s_waitcnt vmcnt(8)
	s_waitcnt lgkmcnt(0)
	s_barrier
	s_setprio 1
	s_waitcnt lgkmcnt(0)
	v_mfma_f32_16x16x32_bf16 v[60:63], v[128:131], v[170:173], v[60:63]
	v_mfma_f32_16x16x32_bf16 v[56:59], v[136:139], v[170:173], v[56:59]
	v_mfma_f32_16x16x32_bf16 v[44:47], v[128:131], v[178:181], v[44:47]
	v_mfma_f32_16x16x32_bf16 v[40:43], v[136:139], v[178:181], v[40:43]
	v_mfma_f32_16x16x32_bf16 v[28:31], v[128:131], v[194:197], v[28:31]
	v_mfma_f32_16x16x32_bf16 v[24:27], v[136:139], v[194:197], v[24:27]
	v_mfma_f32_16x16x32_bf16 v[12:15], v[128:131], v[202:205], v[12:15]
	v_mfma_f32_16x16x32_bf16 v[8:11], v[136:139], v[202:205], v[8:11]
	v_mfma_f32_16x16x32_bf16 v[60:63], v[132:135], v[174:177], v[60:63]
	v_mfma_f32_16x16x32_bf16 v[56:59], v[140:143], v[174:177], v[56:59]
	v_mfma_f32_16x16x32_bf16 v[44:47], v[132:135], v[186:189], v[44:47]
	v_mfma_f32_16x16x32_bf16 v[40:43], v[140:143], v[186:189], v[40:43]
	v_mfma_f32_16x16x32_bf16 v[28:31], v[132:135], v[198:201], v[28:31]
	v_mfma_f32_16x16x32_bf16 v[24:27], v[140:143], v[198:201], v[24:27]
	v_mfma_f32_16x16x32_bf16 v[12:15], v[132:135], v[206:209], v[12:15]
	v_mfma_f32_16x16x32_bf16 v[8:11], v[140:143], v[206:209], v[8:11]
	v_mfma_f32_16x16x32_bf16 v[52:55], v[144:147], v[170:173], v[52:55]
	v_mfma_f32_16x16x32_bf16 v[48:51], v[152:155], v[170:173], v[48:51]
	v_mfma_f32_16x16x32_bf16 v[36:39], v[144:147], v[178:181], v[36:39]
	v_mfma_f32_16x16x32_bf16 v[32:35], v[152:155], v[178:181], v[32:35]
	v_mfma_f32_16x16x32_bf16 v[20:23], v[144:147], v[194:197], v[20:23]
	v_mfma_f32_16x16x32_bf16 v[16:19], v[152:155], v[194:197], v[16:19]
	v_mfma_f32_16x16x32_bf16 v[4:7], v[144:147], v[202:205], v[4:7]
	v_mfma_f32_16x16x32_bf16 v[0:3], v[152:155], v[202:205], v[0:3]
	v_mfma_f32_16x16x32_bf16 v[52:55], v[148:151], v[174:177], v[52:55]
	v_mfma_f32_16x16x32_bf16 v[48:51], v[166:169], v[174:177], v[48:51]
	v_mfma_f32_16x16x32_bf16 v[36:39], v[148:151], v[186:189], v[36:39]
	v_mfma_f32_16x16x32_bf16 v[32:35], v[166:169], v[186:189], v[32:35]
	v_mfma_f32_16x16x32_bf16 v[20:23], v[148:151], v[198:201], v[20:23]
	v_mfma_f32_16x16x32_bf16 v[16:19], v[166:169], v[198:201], v[16:19]
	v_mfma_f32_16x16x32_bf16 v[4:7], v[148:151], v[206:209], v[4:7]
	v_mfma_f32_16x16x32_bf16 v[0:3], v[166:169], v[206:209], v[0:3]
	s_setprio 0
	s_barrier
	s_add_u32 s44, s44, 0x100
	s_addc_u32 s45, s45, 0
	s_add_u32 s19, s19, 0x100
	s_addc_u32 s20, s20, 0
	s_cmp_ge_u32 s66, s73
	s_mov_b32 s46, s66
	s_cbranch_scc0 .LBB0_63
	s_and_b64 vcc, exec, s[56:57]
	s_cbranch_vccz .LBB0_66
	s_barrier

; #define PG8_STAGE(bufoff, gbase, voff) do { _Pragma("unroll") for (int _i = 0; _i < 2; ++_i) \
;         __builtin_amdgcn_global_load_lds((const unsigned*)((const char*)(gbase) + (voff)[_i]), (PG8_LAS unsigned*)(lds + (bufoff) + ldsw + _i * 8192), 16, 0, 0); } while (0)
; #define PG8_LDA(dst, b, h) do { _Pragma("unroll") for (int m = 0; m < 4; ++m) _Pragma("unroll") for (int k = 0; k < 2; ++k) dst[m][k] = *(const PG8_LAS bf16x8*)(lds + PG8_SA(b, h) + aoff + m * 2048 + k * 1024); } while (0)
; #define PG8_LDB(dst, b, h) do { _Pragma("unroll") for (int n = 0; n < 2; ++n) _Pragma("unroll") for (int k = 0; k < 2; ++k) dst[n][k] = *(const PG8_LAS bf16x8*)(lds + PG8_SB(b, h) + boff + n * 2048 + k * 1024); } while (0)
; #define PG8_MMA(ai, bj, At, Bt) do { __builtin_amdgcn_s_setprio(1); _Pragma("unroll") for (int m = 0; m < 4; ++m) _Pragma("unroll") for (int n = 0; n < 2; ++n) _Pragma("unroll") for (int k = 0; k < 2; ++k) \
;         acc[ai][bj][m][n] = __builtin_amdgcn_mfma_f32_16x16x32_bf16(Bt[n][k], At[m][k], acc[ai][bj][m][n], 0, 0, 0); __builtin_amdgcn_s_setprio(0); } while (0)
; #define PG8_WAIT_V(n) asm volatile("s_waitcnt vmcnt(" #n ")" ::: "memory")
; #define PG8_WAIT_L(n) asm volatile("s_waitcnt lgkmcnt(" #n ")" ::: "memory")
; #define PG8_BAR __builtin_amdgcn_s_barrier()
; #define PG8_SCHED __builtin_amdgcn_sched_barrier(0)
; template <class Epi, class Sched, bool ALIGN_EPI = false, bool SP2 = false>
; __device__ __forceinline__ void gemm_phase(PG8_LAS unsigned char* lds, const Gemm g, const Sched& S, const Epi& E) {
;     ...
;             const bool last = (t == nt - 2);
;             const char* a1 = cA + (size_t)(t + 1) * kstep;
;             const char* a2 = last ? nA : cA + (size_t)(t + 2) * kstep; const char* b2 = last ? nB : cB + (size_t)(t + 2) * kstep;
;             const char* a3 = a2 + kstep; const char* b3 = b2 + kstep;
;             if (last && has_next) S.a_ready(nxt);
;             if constexpr (SP2) {
;             PG8_LDB(B0, 0, 0); PG8_LDB(B1, 0, 1); PG8_SCHED; PG8_LDA(At, 0, 0); PG8_STAGE(PG8_SA(1, 1), a1 + hstep, voffA);
;             PG8_WAIT_V(8); PG8_WAIT_L(0); PG8_BAR; PG8_MMA(0, 0, At, B0); PG8_MMA(0, 1, At, B1); PG8_BAR; PG8_SCHED;
;             PG8_LDA(At, 0, 1); PG8_STAGE(PG8_SB(0, 0), b2, voffB); PG8_STAGE(PG8_SB(0, 1), b2 + hstep, voffB); PG8_STAGE(PG8_SA(0, 0), a2, voffA);
.LBB0_200:
	s_add_u32 s10, s56, 0xfffc0080
	s_addc_u32 s11, s57, -1
	s_add_i32 s77, 0, 0x10000
	s_cmp_eq_u32 s76, 12
	s_cselect_b32 s61, s18, s11
	s_cselect_b32 s60, s19, s10
	s_cselect_b32 s59, s20, s51
	s_cselect_b32 s58, s43, s49
	s_add_i32 s10, 0, 0x14000
	v_add_u32_e32 v140, s77, v163
	v_add_u32_e32 v162, s10, v163
	ds_read_b128 v[128:131], v140
	ds_read_b128 v[132:135], v140 offset:1024
	ds_read_b128 v[136:139], v140 offset:2048
	ds_read_b128 v[140:143], v140 offset:3072
	ds_read_b128 v[166:169], v162
	ds_read_b128 v[170:173], v162 offset:1024
	ds_read_b128 v[174:177], v162 offset:2048
	ds_read_b128 v[178:181], v162 offset:3072
	v_lshl_add_u64 v[190:191], s[56:57], 0, v[158:159]
	s_add_i32 m0, s64, 0xc000
	ds_read_b128 v[182:185], v165
	ds_read_b128 v[186:189], v165 offset:1024
	ds_read_b128 v[194:197], v165 offset:2048
	ds_read_b128 v[198:201], v165 offset:3072
	ds_read_b128 v[202:205], v165 offset:4096
	ds_read_b128 v[206:209], v165 offset:5120
	ds_read_b128 v[210:213], v165 offset:6144
	ds_read_b128 v[214:217], v165 offset:7168
	global_load_lds_dwordx4 v[190:191], off
	v_lshl_add_u64 v[190:191], s[56:57], 0, v[160:161]
	s_add_i32 m0, s64, 0xe000
	s_nop 0
	global_load_lds_dwordx4 v[190:191], off
	s_waitcnt vmcnt(8)
	s_waitcnt lgkmcnt(0)
	s_barrier
	s_setprio 1
	s_waitcnt lgkmcnt(0)
	v_mfma_f32_16x16x32_bf16 v[124:127], v[128:131], v[182:185], v[124:127]
	v_mfma_f32_16x16x32_bf16 v[120:123], v[136:139], v[182:185], v[120:123]
	v_mfma_f32_16x16x32_bf16 v[112:115], v[128:131], v[194:197], v[112:115]
	v_mfma_f32_16x16x32_bf16 v[104:107], v[136:139], v[194:197], v[104:107]
	v_mfma_f32_16x16x32_bf16 v[96:99], v[128:131], v[202:205], v[96:99]
	v_mfma_f32_16x16x32_bf16 v[88:91], v[136:139], v[202:205], v[88:91]
	v_mfma_f32_16x16x32_bf16 v[80:83], v[128:131], v[210:213], v[80:83]
	v_mfma_f32_16x16x32_bf16 v[72:75], v[136:139], v[210:213], v[72:75]
	v_mfma_f32_16x16x32_bf16 v[124:127], v[132:135], v[186:189], v[124:127]
	v_mfma_f32_16x16x32_bf16 v[120:123], v[140:143], v[186:189], v[120:123]
	v_mfma_f32_16x16x32_bf16 v[112:115], v[132:135], v[198:201], v[112:115]
	v_mfma_f32_16x16x32_bf16 v[104:107], v[140:143], v[198:201], v[104:107]
	v_mfma_f32_16x16x32_bf16 v[96:99], v[132:135], v[206:209], v[96:99]
	v_mfma_f32_16x16x32_bf16 v[88:91], v[140:143], v[206:209], v[88:91]
	v_mfma_f32_16x16x32_bf16 v[80:83], v[132:135], v[214:217], v[80:83]
	v_mfma_f32_16x16x32_bf16 v[72:75], v[140:143], v[214:217], v[72:75]
	v_mfma_f32_16x16x32_bf16 v[116:119], v[166:169], v[182:185], v[116:119]
	v_mfma_f32_16x16x32_bf16 v[108:111], v[174:177], v[182:185], v[108:111]
	v_mfma_f32_16x16x32_bf16 v[100:103], v[166:169], v[194:197], v[100:103]
	v_mfma_f32_16x16x32_bf16 v[92:95], v[174:177], v[194:197], v[92:95]
	v_mfma_f32_16x16x32_bf16 v[84:87], v[166:169], v[202:205], v[84:87]
	v_mfma_f32_16x16x32_bf16 v[76:79], v[174:177], v[202:205], v[76:79]
	v_mfma_f32_16x16x32_bf16 v[68:71], v[166:169], v[210:213], v[68:71]
	v_mfma_f32_16x16x32_bf16 v[64:67], v[174:177], v[210:213], v[64:67]
	v_mfma_f32_16x16x32_bf16 v[116:119], v[170:173], v[186:189], v[116:119]
	v_mfma_f32_16x16x32_bf16 v[108:111], v[178:181], v[186:189], v[108:111]
	v_mfma_f32_16x16x32_bf16 v[100:103], v[170:173], v[198:201], v[100:103]
	v_mfma_f32_16x16x32_bf16 v[92:95], v[178:181], v[198:201], v[92:95]
	v_mfma_f32_16x16x32_bf16 v[84:87], v[170:173], v[206:209], v[84:87]
	v_mfma_f32_16x16x32_bf16 v[76:79], v[178:181], v[206:209], v[76:79]
	v_mfma_f32_16x16x32_bf16 v[68:71], v[170:173], v[214:217], v[68:71]
	v_mfma_f32_16x16x32_bf16 v[64:67], v[178:181], v[214:217], v[64:67]
	s_setprio 0
	s_barrier
	s_add_i32 s11, s77, s63
	v_lshl_add_u64 v[190:191], s[58:59], 0, v[146:147]
	s_mov_b32 m0, s11
	ds_read_b128 v[182:185], v165 offset:16384
	ds_read_b128 v[186:189], v165 offset:17408
	ds_read_b128 v[194:197], v165 offset:18432
	ds_read_b128 v[198:201], v165 offset:19456
	ds_read_b128 v[202:205], v165 offset:20480
	ds_read_b128 v[206:209], v165 offset:21504
	ds_read_b128 v[210:213], v165 offset:22528
	ds_read_b128 v[214:217], v165 offset:23552
	global_load_lds_dwordx4 v[190:191], off
	s_add_i32 m0, s11, 0x2000
	s_add_u32 s78, s58, 0x40000
	v_lshl_add_u64 v[218:219], s[58:59], 0, v[150:151]
	s_addc_u32 s79, s59, 0
	s_add_i32 s10, s10, s63
	global_load_lds_dwordx4 v[218:219], off
	v_lshl_add_u64 v[220:221], s[78:79], 0, v[146:147]
	s_mov_b32 m0, s10
	v_lshl_add_u64 v[222:223], s[60:61], 0, v[148:149]
	global_load_lds_dwordx4 v[220:221], off
	v_lshl_add_u64 v[220:221], s[78:79], 0, v[150:151]
	s_add_i32 m0, s10, 0x2000
	s_nop 0
	global_load_lds_dwordx4 v[220:221], off
	v_lshl_add_u64 v[220:221], s[60:61], 0, v[144:145]
	s_mov_b32 m0, s64
	s_nop 0
	global_load_lds_dwordx4 v[220:221], off
	s_mov_b32 m0, s65
	s_nop 0
	global_load_lds_dwordx4 v[222:223], off
	s_waitcnt vmcnt(8)
	s_waitcnt lgkmcnt(0)
	s_barrier
; #define PG8_STAGE(bufoff, gbase, voff) do { _Pragma("unroll") for (int _i = 0; _i < 2; ++_i) \
;         __builtin_amdgcn_global_load_lds((const unsigned*)((const char*)(gbase) + (voff)[_i]), (PG8_LAS unsigned*)(lds + (bufoff) + ldsw + _i * 8192), 16, 0, 0); } while (0)
; #define PG8_LDA(dst, b, h) do { _Pragma("unroll") for (int m = 0; m < 4; ++m) _Pragma("unroll") for (int k = 0; k < 2; ++k) dst[m][k] = *(const PG8_LAS bf16x8*)(lds + PG8_SA(b, h) + aoff + m * 2048 + k * 1024); } while (0)
; #define PG8_LDB(dst, b, h) do { _Pragma("unroll") for (int n = 0; n < 2; ++n) _Pragma("unroll") for (int k = 0; k < 2; ++k) dst[n][k] = *(const PG8_LAS bf16x8*)(lds + PG8_SB(b, h) + boff + n * 2048 + k * 1024); } while (0)
; #define PG8_MMA(ai, bj, At, Bt) do { __builtin_amdgcn_s_setprio(1); _Pragma("unroll") for (int m = 0; m < 4; ++m) _Pragma("unroll") for (int n = 0; n < 2; ++n) _Pragma("unroll") for (int k = 0; k < 2; ++k) \
;         acc[ai][bj][m][n] = __builtin_amdgcn_mfma_f32_16x16x32_bf16(Bt[n][k], At[m][k], acc[ai][bj][m][n], 0, 0, 0); __builtin_amdgcn_s_setprio(0); } while (0)
; #define PG8_WAIT_V(n) asm volatile("s_waitcnt vmcnt(" #n ")" ::: "memory")
; #define PG8_WAIT_L(n) asm volatile("s_waitcnt lgkmcnt(" #n ")" ::: "memory")
; #define PG8_BAR __builtin_amdgcn_s_barrier()
; #define PG8_SCHED __builtin_amdgcn_sched_barrier(0)
; template <class Epi, class Sched, bool ALIGN_EPI = false, bool SP2 = false>
; __device__ __forceinline__ void gemm_phase(PG8_LAS unsigned char* lds, const Gemm g, const Sched& S, const Epi& E) {
;     ...
;             PG8_WAIT_V(8); PG8_WAIT_L(0); PG8_BAR; PG8_MMA(1, 0, At, B0); PG8_MMA(1, 1, At, B1); PG8_BAR; PG8_SCHED;
;             PG8_LDB(B0, 1, 0); PG8_LDB(B1, 1, 1); PG8_SCHED; PG8_LDA(At, 1, 0); PG8_STAGE(PG8_SA(0, 1), a2 + hstep, voffA);
;             PG8_WAIT_V(8); PG8_WAIT_L(0); PG8_BAR; PG8_MMA(0, 0, At, B0); PG8_MMA(0, 1, At, B1); PG8_BAR; PG8_SCHED;
	s_setprio 1
	s_waitcnt lgkmcnt(0)
	v_mfma_f32_16x16x32_bf16 v[60:63], v[128:131], v[182:185], v[60:63]
	v_mfma_f32_16x16x32_bf16 v[56:59], v[136:139], v[182:185], v[56:59]
	v_mfma_f32_16x16x32_bf16 v[48:51], v[128:131], v[194:197], v[48:51]
	v_mfma_f32_16x16x32_bf16 v[40:43], v[136:139], v[194:197], v[40:43]
	v_mfma_f32_16x16x32_bf16 v[32:35], v[128:131], v[202:205], v[32:35]
	v_mfma_f32_16x16x32_bf16 v[24:27], v[136:139], v[202:205], v[24:27]
	v_mfma_f32_16x16x32_bf16 v[16:19], v[128:131], v[210:213], v[16:19]
	v_mfma_f32_16x16x32_bf16 v[8:11], v[136:139], v[210:213], v[8:11]
	v_mfma_f32_16x16x32_bf16 v[60:63], v[132:135], v[186:189], v[60:63]
	v_mfma_f32_16x16x32_bf16 v[56:59], v[140:143], v[186:189], v[56:59]
	v_mfma_f32_16x16x32_bf16 v[48:51], v[132:135], v[198:201], v[48:51]
	v_mfma_f32_16x16x32_bf16 v[40:43], v[140:143], v[198:201], v[40:43]
	v_mfma_f32_16x16x32_bf16 v[32:35], v[132:135], v[206:209], v[32:35]
	v_mfma_f32_16x16x32_bf16 v[24:27], v[140:143], v[206:209], v[24:27]
	v_mfma_f32_16x16x32_bf16 v[16:19], v[132:135], v[214:217], v[16:19]
	v_mfma_f32_16x16x32_bf16 v[8:11], v[140:143], v[214:217], v[8:11]
	v_mfma_f32_16x16x32_bf16 v[52:55], v[166:169], v[182:185], v[52:55]
	v_mfma_f32_16x16x32_bf16 v[44:47], v[174:177], v[182:185], v[44:47]
	v_mfma_f32_16x16x32_bf16 v[36:39], v[166:169], v[194:197], v[36:39]
	v_mfma_f32_16x16x32_bf16 v[28:31], v[174:177], v[194:197], v[28:31]
	v_mfma_f32_16x16x32_bf16 v[20:23], v[166:169], v[202:205], v[20:23]
	v_mfma_f32_16x16x32_bf16 v[12:15], v[174:177], v[202:205], v[12:15]
	v_mfma_f32_16x16x32_bf16 v[4:7], v[166:169], v[210:213], v[4:7]
	v_mfma_f32_16x16x32_bf16 v[0:3], v[174:177], v[210:213], v[0:3]
	v_mfma_f32_16x16x32_bf16 v[52:55], v[170:173], v[186:189], v[52:55]
	v_mfma_f32_16x16x32_bf16 v[44:47], v[178:181], v[186:189], v[44:47]
	v_mfma_f32_16x16x32_bf16 v[36:39], v[170:173], v[198:201], v[36:39]
	v_mfma_f32_16x16x32_bf16 v[28:31], v[178:181], v[198:201], v[28:31]
	v_mfma_f32_16x16x32_bf16 v[20:23], v[170:173], v[206:209], v[20:23]
	v_mfma_f32_16x16x32_bf16 v[12:15], v[178:181], v[206:209], v[12:15]
	v_mfma_f32_16x16x32_bf16 v[4:7], v[170:173], v[214:217], v[4:7]
	v_mfma_f32_16x16x32_bf16 v[0:3], v[178:181], v[214:217], v[0:3]
	s_setprio 0
	s_barrier
	s_add_i32 s10, 0, 0x18000
	s_add_i32 s11, 0, 0x1c000
	v_add_u32_e32 v140, s10, v163
	v_add_u32_e32 v162, s11, v163
	ds_read_b128 v[128:131], v140
	ds_read_b128 v[132:135], v140 offset:1024
	ds_read_b128 v[136:139], v140 offset:2048
	ds_read_b128 v[140:143], v140 offset:3072
	ds_read_b128 v[166:169], v162
	ds_read_b128 v[170:173], v162 offset:1024
	ds_read_b128 v[174:177], v162 offset:2048
	ds_read_b128 v[178:181], v162 offset:3072
	s_add_u32 s60, s60, 0x40000
	s_addc_u32 s61, s61, 0
	s_mov_b32 m0, s66
	v_lshl_add_u64 v[224:225], s[60:61], 0, v[144:145]
	ds_read_b128 v[182:185], v165 offset:32768
	ds_read_b128 v[186:189], v165 offset:33792
	ds_read_b128 v[194:197], v165 offset:34816
	ds_read_b128 v[198:201], v165 offset:35840
	ds_read_b128 v[202:205], v165 offset:36864
	ds_read_b128 v[206:209], v165 offset:37888
	ds_read_b128 v[210:213], v165 offset:38912
	ds_read_b128 v[214:217], v165 offset:39936
	global_load_lds_dwordx4 v[224:225], off
	v_lshl_add_u64 v[224:225], s[60:61], 0, v[148:149]
	s_mov_b32 m0, s67
	s_nop 0
	global_load_lds_dwordx4 v[224:225], off
	s_waitcnt vmcnt(8)
	s_waitcnt lgkmcnt(0)
	s_barrier
	s_setprio 1
	s_waitcnt lgkmcnt(0)
	v_mfma_f32_16x16x32_bf16 v[124:127], v[128:131], v[182:185], v[124:127]
	v_mfma_f32_16x16x32_bf16 v[120:123], v[136:139], v[182:185], v[120:123]
	v_mfma_f32_16x16x32_bf16 v[112:115], v[128:131], v[194:197], v[112:115]
	v_mfma_f32_16x16x32_bf16 v[104:107], v[136:139], v[194:197], v[104:107]
	v_mfma_f32_16x16x32_bf16 v[96:99], v[128:131], v[202:205], v[96:99]
	v_mfma_f32_16x16x32_bf16 v[88:91], v[136:139], v[202:205], v[88:91]
	v_mfma_f32_16x16x32_bf16 v[80:83], v[128:131], v[210:213], v[80:83]
	v_mfma_f32_16x16x32_bf16 v[72:75], v[136:139], v[210:213], v[72:75]
	v_mfma_f32_16x16x32_bf16 v[124:127], v[132:135], v[186:189], v[124:127]
	v_mfma_f32_16x16x32_bf16 v[120:123], v[140:143], v[186:189], v[120:123]
	v_mfma_f32_16x16x32_bf16 v[112:115], v[132:135], v[198:201], v[112:115]
	v_mfma_f32_16x16x32_bf16 v[104:107], v[140:143], v[198:201], v[104:107]
	v_mfma_f32_16x16x32_bf16 v[96:99], v[132:135], v[206:209], v[96:99]
	v_mfma_f32_16x16x32_bf16 v[88:91], v[140:143], v[206:209], v[88:91]
	v_mfma_f32_16x16x32_bf16 v[80:83], v[132:135], v[214:217], v[80:83]
	v_mfma_f32_16x16x32_bf16 v[72:75], v[140:143], v[214:217], v[72:75]
	v_mfma_f32_16x16x32_bf16 v[116:119], v[166:169], v[182:185], v[116:119]
	v_mfma_f32_16x16x32_bf16 v[108:111], v[174:177], v[182:185], v[108:111]
	v_mfma_f32_16x16x32_bf16 v[100:103], v[166:169], v[194:197], v[100:103]
	v_mfma_f32_16x16x32_bf16 v[92:95], v[174:177], v[194:197], v[92:95]
	v_mfma_f32_16x16x32_bf16 v[84:87], v[166:169], v[202:205], v[84:87]
	v_mfma_f32_16x16x32_bf16 v[76:79], v[174:177], v[202:205], v[76:79]
	v_mfma_f32_16x16x32_bf16 v[68:71], v[166:169], v[210:213], v[68:71]
	v_mfma_f32_16x16x32_bf16 v[64:67], v[174:177], v[210:213], v[64:67]
	v_mfma_f32_16x16x32_bf16 v[116:119], v[170:173], v[186:189], v[116:119]
	v_mfma_f32_16x16x32_bf16 v[108:111], v[178:181], v[186:189], v[108:111]
	v_mfma_f32_16x16x32_bf16 v[100:103], v[170:173], v[198:201], v[100:103]
	v_mfma_f32_16x16x32_bf16 v[92:95], v[178:181], v[198:201], v[92:95]
	v_mfma_f32_16x16x32_bf16 v[84:87], v[170:173], v[206:209], v[84:87]
	v_mfma_f32_16x16x32_bf16 v[76:79], v[178:181], v[206:209], v[76:79]
	v_mfma_f32_16x16x32_bf16 v[68:71], v[170:173], v[214:217], v[68:71]
	v_mfma_f32_16x16x32_bf16 v[64:67], v[178:181], v[214:217], v[64:67]
	s_setprio 0
	s_barrier
; #define PG8_STAGE(bufoff, gbase, voff) do { _Pragma("unroll") for (int _i = 0; _i < 2; ++_i) \
;         __builtin_amdgcn_global_load_lds((const unsigned*)((const char*)(gbase) + (voff)[_i]), (PG8_LAS unsigned*)(lds + (bufoff) + ldsw + _i * 8192), 16, 0, 0); } while (0)
; #define PG8_LDA(dst, b, h) do { _Pragma("unroll") for (int m = 0; m < 4; ++m) _Pragma("unroll") for (int k = 0; k < 2; ++k) dst[m][k] = *(const PG8_LAS bf16x8*)(lds + PG8_SA(b, h) + aoff + m * 2048 + k * 1024); } while (0)
; #define PG8_MMA(ai, bj, At, Bt) do { __builtin_amdgcn_s_setprio(1); _Pragma("unroll") for (int m = 0; m < 4; ++m) _Pragma("unroll") for (int n = 0; n < 2; ++n) _Pragma("unroll") for (int k = 0; k < 2; ++k) \
;         acc[ai][bj][m][n] = __builtin_amdgcn_mfma_f32_16x16x32_bf16(Bt[n][k], At[m][k], acc[ai][bj][m][n], 0, 0, 0); __builtin_amdgcn_s_setprio(0); } while (0)
; #define PG8_WAIT_V(n) asm volatile("s_waitcnt vmcnt(" #n ")" ::: "memory")
; #define PG8_WAIT_L(n) asm volatile("s_waitcnt lgkmcnt(" #n ")" ::: "memory")
; #define PG8_BAR __builtin_amdgcn_s_barrier()
; #define PG8_SCHED __builtin_amdgcn_sched_barrier(0)
; template <class Epi, class Sched, bool ALIGN_EPI = false, bool SP2 = false>
; __device__ __forceinline__ void gemm_phase(PG8_LAS unsigned char* lds, const Gemm g, const Sched& S, const Epi& E) {
;     ...
;             PG8_LDA(At, 1, 1); PG8_STAGE(PG8_SB(1, 0), b3, voffB); PG8_STAGE(PG8_SB(1, 1), b3 + hstep, voffB); PG8_STAGE(PG8_SA(1, 0), a3, voffA);
;             PG8_WAIT_V(8); PG8_WAIT_L(0); PG8_BAR; PG8_MMA(1, 0, At, B0); PG8_MMA(1, 1, At, B1); PG8_BAR; PG8_SCHED;
;     ...
;         if constexpr (ALIGN_EPI) { if (wr == 0) PG8_BAR; }
	s_add_i32 s10, s10, s63
	v_lshl_add_u64 v[190:191], v[190:191], 0, s[36:37]
	s_mov_b32 m0, s10
	ds_read_b128 v[182:185], v165 offset:49152
	ds_read_b128 v[186:189], v165 offset:50176
	ds_read_b128 v[194:197], v165 offset:51200
	ds_read_b128 v[198:201], v165 offset:52224
	ds_read_b128 v[202:205], v165 offset:53248
	ds_read_b128 v[206:209], v165 offset:54272
	ds_read_b128 v[210:213], v165 offset:55296
	ds_read_b128 v[214:217], v165 offset:56320
	global_load_lds_dwordx4 v[190:191], off
	s_add_i32 m0, s10, 0x2000
	s_add_u32 s58, s58, 0x40080
	v_lshl_add_u64 v[190:191], v[218:219], 0, s[36:37]
	s_addc_u32 s59, s59, 0
	s_add_i32 s10, s11, s63
	global_load_lds_dwordx4 v[190:191], off
	v_lshl_add_u64 v[190:191], s[58:59], 0, v[146:147]
	s_mov_b32 m0, s10
	s_nop 0
	global_load_lds_dwordx4 v[190:191], off
	v_lshl_add_u64 v[190:191], s[58:59], 0, v[150:151]
	s_add_i32 m0, s10, 0x2000
	s_nop 0
	global_load_lds_dwordx4 v[190:191], off
	v_lshl_add_u64 v[190:191], v[220:221], 0, s[36:37]
	s_mov_b32 m0, s70
	s_nop 0
	global_load_lds_dwordx4 v[190:191], off
	v_lshl_add_u64 v[190:191], v[222:223], 0, s[36:37]
	s_mov_b32 m0, s71
	s_nop 0
	global_load_lds_dwordx4 v[190:191], off
	s_waitcnt vmcnt(8)
	s_waitcnt lgkmcnt(0)
	s_barrier
	s_setprio 1
	s_waitcnt lgkmcnt(0)
	v_mfma_f32_16x16x32_bf16 v[60:63], v[128:131], v[182:185], v[60:63]
	v_mfma_f32_16x16x32_bf16 v[56:59], v[136:139], v[182:185], v[56:59]
	v_mfma_f32_16x16x32_bf16 v[48:51], v[128:131], v[194:197], v[48:51]
	v_mfma_f32_16x16x32_bf16 v[40:43], v[136:139], v[194:197], v[40:43]
	v_mfma_f32_16x16x32_bf16 v[32:35], v[128:131], v[202:205], v[32:35]
	v_mfma_f32_16x16x32_bf16 v[24:27], v[136:139], v[202:205], v[24:27]
	v_mfma_f32_16x16x32_bf16 v[16:19], v[128:131], v[210:213], v[16:19]
	v_mfma_f32_16x16x32_bf16 v[8:11], v[136:139], v[210:213], v[8:11]
	v_mfma_f32_16x16x32_bf16 v[60:63], v[132:135], v[186:189], v[60:63]
	v_mfma_f32_16x16x32_bf16 v[56:59], v[140:143], v[186:189], v[56:59]
	v_mfma_f32_16x16x32_bf16 v[48:51], v[132:135], v[198:201], v[48:51]
	v_mfma_f32_16x16x32_bf16 v[40:43], v[140:143], v[198:201], v[40:43]
	v_mfma_f32_16x16x32_bf16 v[32:35], v[132:135], v[206:209], v[32:35]
	v_mfma_f32_16x16x32_bf16 v[24:27], v[140:143], v[206:209], v[24:27]
	v_mfma_f32_16x16x32_bf16 v[16:19], v[132:135], v[214:217], v[16:19]
	v_mfma_f32_16x16x32_bf16 v[8:11], v[140:143], v[214:217], v[8:11]
	v_mfma_f32_16x16x32_bf16 v[52:55], v[166:169], v[182:185], v[52:55]
	v_mfma_f32_16x16x32_bf16 v[44:47], v[174:177], v[182:185], v[44:47]
	v_mfma_f32_16x16x32_bf16 v[36:39], v[166:169], v[194:197], v[36:39]
	v_mfma_f32_16x16x32_bf16 v[28:31], v[174:177], v[194:197], v[28:31]
	v_mfma_f32_16x16x32_bf16 v[20:23], v[166:169], v[202:205], v[20:23]
	v_mfma_f32_16x16x32_bf16 v[12:15], v[174:177], v[202:205], v[12:15]
	v_mfma_f32_16x16x32_bf16 v[4:7], v[166:169], v[210:213], v[4:7]
	v_mfma_f32_16x16x32_bf16 v[0:3], v[174:177], v[210:213], v[0:3]
	v_mfma_f32_16x16x32_bf16 v[52:55], v[170:173], v[186:189], v[52:55]
	v_mfma_f32_16x16x32_bf16 v[44:47], v[178:181], v[186:189], v[44:47]
	v_mfma_f32_16x16x32_bf16 v[36:39], v[170:173], v[198:201], v[36:39]
	v_mfma_f32_16x16x32_bf16 v[28:31], v[178:181], v[198:201], v[28:31]
	v_mfma_f32_16x16x32_bf16 v[20:23], v[170:173], v[206:209], v[20:23]
	v_mfma_f32_16x16x32_bf16 v[12:15], v[178:181], v[206:209], v[12:15]
	v_mfma_f32_16x16x32_bf16 v[4:7], v[170:173], v[214:217], v[4:7]
	v_mfma_f32_16x16x32_bf16 v[0:3], v[178:181], v[214:217], v[0:3]
	s_setprio 0
	s_barrier
	s_add_i32 s76, s76, 2
	s_add_u32 s56, s56, 0x100
	s_addc_u32 s57, s57, 0
	s_add_u32 s49, s49, 0x100
	s_addc_u32 s51, s51, 0
	s_cmp_gt_u32 s76, 13
	s_cbranch_scc0 .LBB0_200
	s_and_b64 vcc, exec, s[44:45]
	s_cbranch_vccz .LBB0_203
	s_barrier

; #define PG8_STAGE(bufoff, gbase, voff) do { _Pragma("unroll") for (int _i = 0; _i < 2; ++_i) \
;         __builtin_amdgcn_global_load_lds((const unsigned*)((const char*)(gbase) + (voff)[_i]), (PG8_LAS unsigned*)(lds + (bufoff) + ldsw + _i * 8192), 16, 0, 0); } while (0)
; #define PG8_LDA(dst, b, h) do { _Pragma("unroll") for (int m = 0; m < 4; ++m) _Pragma("unroll") for (int k = 0; k < 2; ++k) dst[m][k] = *(const PG8_LAS bf16x8*)(lds + PG8_SA(b, h) + aoff + m * 2048 + k * 1024); } while (0)
; #define PG8_LDB(dst, b, h) do { _Pragma("unroll") for (int n = 0; n < 2; ++n) _Pragma("unroll") for (int k = 0; k < 2; ++k) dst[n][k] = *(const PG8_LAS bf16x8*)(lds + PG8_SB(b, h) + boff + n * 2048 + k * 1024); } while (0)
; #define PG8_MMA(ai, bj, At, Bt) do { __builtin_amdgcn_s_setprio(1); _Pragma("unroll") for (int m = 0; m < 4; ++m) _Pragma("unroll") for (int n = 0; n < 2; ++n) _Pragma("unroll") for (int k = 0; k < 2; ++k) \
;         acc[ai][bj][m][n] = __builtin_amdgcn_mfma_f32_16x16x32_bf16(Bt[n][k], At[m][k], acc[ai][bj][m][n], 0, 0, 0); __builtin_amdgcn_s_setprio(0); } while (0)
; #define PG8_WAIT_V(n) asm volatile("s_waitcnt vmcnt(" #n ")" ::: "memory")
; #define PG8_WAIT_L(n) asm volatile("s_waitcnt lgkmcnt(" #n ")" ::: "memory")
; #define PG8_BAR __builtin_amdgcn_s_barrier()
; #define PG8_SCHED __builtin_amdgcn_sched_barrier(0)
; template <class Epi, class Sched, bool ALIGN_EPI = false, bool SP2 = false>
; __device__ __forceinline__ void gemm_phase(PG8_LAS unsigned char* lds, const Gemm g, const Sched& S, const Epi& E) {
;     ...
;             const bool last = (t == nt - 2);
;             const char* a1 = cA + (size_t)(t + 1) * kstep;
;             const char* a2 = last ? nA : cA + (size_t)(t + 2) * kstep; const char* b2 = last ? nB : cB + (size_t)(t + 2) * kstep;
;             const char* a3 = a2 + kstep; const char* b3 = b2 + kstep;
;             if (last && has_next) S.a_ready(nxt);
;             if constexpr (SP2) {
;             PG8_LDB(B0, 0, 0); PG8_LDB(B1, 0, 1); PG8_SCHED; PG8_LDA(At, 0, 0); PG8_STAGE(PG8_SA(1, 1), a1 + hstep, voffA);
;             PG8_WAIT_V(8); PG8_WAIT_L(0); PG8_BAR; PG8_MMA(0, 0, At, B0); PG8_MMA(0, 1, At, B1); PG8_BAR; PG8_SCHED;
;             PG8_LDA(At, 0, 1); PG8_STAGE(PG8_SB(0, 0), b2, voffB); PG8_STAGE(PG8_SB(0, 1), b2 + hstep, voffB); PG8_STAGE(PG8_SA(0, 0), a2, voffA);
.LBB0_488:
	s_add_u32 s10, s34, 0xfffc0080
	s_addc_u32 s11, s35, -1
	s_add_i32 s77, 0, 0x10000
	s_cmp_eq_u32 s76, 4
	s_cselect_b32 s53, s45, s11
	s_cselect_b32 s52, s44, s10
	s_cselect_b32 s51, s49, s75
	s_cselect_b32 s50, s48, s19
	s_add_i32 s78, 0, 0x14000
	v_add_u32_e32 v140, s77, v246
	v_add_u32_e32 v156, s77, v246
	v_add_u32_e32 v156, 0x1000, v156
	ds_read_b128 v[128:131], v140
	ds_read_b128 v[132:135], v140 offset:1024
	ds_read_b128 v[136:139], v140 offset:2048
	ds_read_b128 v[140:143], v140 offset:3072
	ds_read_b128 v[144:147], v156
	ds_read_b128 v[148:151], v156 offset:1024
	ds_read_b128 v[152:155], v156 offset:2048
	ds_read_b128 v[156:159], v156 offset:3072
	v_lshl_add_u64 v[208:209], s[34:35], 0, v[204:205]
	s_add_i32 m0, s55, 0xc000
	ds_read_b128 v[160:163], v249
	ds_read_b128 v[164:167], v249 offset:1024
	ds_read_b128 v[168:171], v249 offset:2048
	ds_read_b128 v[172:175], v249 offset:3072
	ds_read_b128 v[176:179], v249 offset:4096
	ds_read_b128 v[180:183], v249 offset:5120
	ds_read_b128 v[184:187], v249 offset:6144
	ds_read_b128 v[188:191], v249 offset:7168
	global_load_lds_dwordx4 v[208:209], off
	v_lshl_add_u64 v[208:209], s[34:35], 0, v[206:207]
	s_add_i32 m0, s55, 0xe000
	s_nop 0
	global_load_lds_dwordx4 v[208:209], off
	s_waitcnt vmcnt(8)
	s_waitcnt lgkmcnt(0)
	s_barrier
	s_setprio 1
	s_waitcnt lgkmcnt(0)
	v_mfma_f32_16x16x32_bf16 v[124:127], v[128:131], v[160:163], v[124:127]
	v_mfma_f32_16x16x32_bf16 v[120:123], v[136:139], v[160:163], v[120:123]
	v_mfma_f32_16x16x32_bf16 v[116:119], v[128:131], v[168:171], v[116:119]
	v_mfma_f32_16x16x32_bf16 v[112:115], v[136:139], v[168:171], v[112:115]
	v_mfma_f32_16x16x32_bf16 v[108:111], v[128:131], v[176:179], v[108:111]
	v_mfma_f32_16x16x32_bf16 v[104:107], v[136:139], v[176:179], v[104:107]
	v_mfma_f32_16x16x32_bf16 v[100:103], v[128:131], v[184:187], v[100:103]
	v_mfma_f32_16x16x32_bf16 v[96:99], v[136:139], v[184:187], v[96:99]
	v_mfma_f32_16x16x32_bf16 v[124:127], v[132:135], v[164:167], v[124:127]
	v_mfma_f32_16x16x32_bf16 v[120:123], v[140:143], v[164:167], v[120:123]
	v_mfma_f32_16x16x32_bf16 v[116:119], v[132:135], v[172:175], v[116:119]
	v_mfma_f32_16x16x32_bf16 v[112:115], v[140:143], v[172:175], v[112:115]
	v_mfma_f32_16x16x32_bf16 v[108:111], v[132:135], v[180:183], v[108:111]
	v_mfma_f32_16x16x32_bf16 v[104:107], v[140:143], v[180:183], v[104:107]
	v_mfma_f32_16x16x32_bf16 v[100:103], v[132:135], v[188:191], v[100:103]
	v_mfma_f32_16x16x32_bf16 v[96:99], v[140:143], v[188:191], v[96:99]
	v_mfma_f32_16x16x32_bf16 v[92:95], v[144:147], v[160:163], v[92:95]
	v_mfma_f32_16x16x32_bf16 v[88:91], v[152:155], v[160:163], v[88:91]
	v_mfma_f32_16x16x32_bf16 v[84:87], v[144:147], v[168:171], v[84:87]
	v_mfma_f32_16x16x32_bf16 v[80:83], v[152:155], v[168:171], v[80:83]
	v_mfma_f32_16x16x32_bf16 v[76:79], v[144:147], v[176:179], v[76:79]
	v_mfma_f32_16x16x32_bf16 v[72:75], v[152:155], v[176:179], v[72:75]
	v_mfma_f32_16x16x32_bf16 v[68:71], v[144:147], v[184:187], v[68:71]
	v_mfma_f32_16x16x32_bf16 v[64:67], v[152:155], v[184:187], v[64:67]
	v_mfma_f32_16x16x32_bf16 v[92:95], v[148:151], v[164:167], v[92:95]
	v_mfma_f32_16x16x32_bf16 v[88:91], v[156:159], v[164:167], v[88:91]
	v_mfma_f32_16x16x32_bf16 v[84:87], v[148:151], v[172:175], v[84:87]
	v_mfma_f32_16x16x32_bf16 v[80:83], v[156:159], v[172:175], v[80:83]
	v_mfma_f32_16x16x32_bf16 v[76:79], v[148:151], v[180:183], v[76:79]
	v_mfma_f32_16x16x32_bf16 v[72:75], v[156:159], v[180:183], v[72:75]
	v_mfma_f32_16x16x32_bf16 v[68:71], v[148:151], v[188:191], v[68:71]
	v_mfma_f32_16x16x32_bf16 v[64:67], v[156:159], v[188:191], v[64:67]
	s_setprio 0
	s_barrier
	s_add_i32 s10, s77, s14
	v_lshl_add_u64 v[208:209], s[50:51], 0, v[198:199]
	s_mov_b32 m0, s10
	ds_read_b128 v[160:163], v249 offset:16384
	ds_read_b128 v[164:167], v249 offset:17408
	ds_read_b128 v[168:171], v249 offset:18432
	ds_read_b128 v[172:175], v249 offset:19456
	ds_read_b128 v[176:179], v249 offset:20480
	ds_read_b128 v[180:183], v249 offset:21504
	ds_read_b128 v[184:187], v249 offset:22528
	ds_read_b128 v[188:191], v249 offset:23552
	global_load_lds_dwordx4 v[208:209], off
	s_add_i32 m0, s10, 0x2000
	s_add_u32 s10, s50, 0x40000
	v_lshl_add_u64 v[210:211], s[50:51], 0, v[194:195]
	s_addc_u32 s11, s51, 0
	s_add_i32 s77, s78, s14
	global_load_lds_dwordx4 v[210:211], off
	v_lshl_add_u64 v[212:213], s[10:11], 0, v[198:199]
	s_mov_b32 m0, s77
	v_lshl_add_u64 v[214:215], s[52:53], 0, v[196:197]
	global_load_lds_dwordx4 v[212:213], off
	v_lshl_add_u64 v[212:213], s[10:11], 0, v[194:195]
	s_add_i32 m0, s77, 0x2000
	s_nop 0
	global_load_lds_dwordx4 v[212:213], off
	v_lshl_add_u64 v[212:213], s[52:53], 0, v[200:201]
	s_mov_b32 m0, s55
	s_nop 0
	global_load_lds_dwordx4 v[212:213], off
	s_mov_b32 m0, s58
	s_nop 0
	global_load_lds_dwordx4 v[214:215], off
	s_waitcnt vmcnt(8)
	s_waitcnt lgkmcnt(0)
	s_barrier
; #define PG8_STAGE(bufoff, gbase, voff) do { _Pragma("unroll") for (int _i = 0; _i < 2; ++_i) \
;         __builtin_amdgcn_global_load_lds((const unsigned*)((const char*)(gbase) + (voff)[_i]), (PG8_LAS unsigned*)(lds + (bufoff) + ldsw + _i * 8192), 16, 0, 0); } while (0)
; #define PG8_LDA(dst, b, h) do { _Pragma("unroll") for (int m = 0; m < 4; ++m) _Pragma("unroll") for (int k = 0; k < 2; ++k) dst[m][k] = *(const PG8_LAS bf16x8*)(lds + PG8_SA(b, h) + aoff + m * 2048 + k * 1024); } while (0)
; #define PG8_LDB(dst, b, h) do { _Pragma("unroll") for (int n = 0; n < 2; ++n) _Pragma("unroll") for (int k = 0; k < 2; ++k) dst[n][k] = *(const PG8_LAS bf16x8*)(lds + PG8_SB(b, h) + boff + n * 2048 + k * 1024); } while (0)
; #define PG8_MMA(ai, bj, At, Bt) do { __builtin_amdgcn_s_setprio(1); _Pragma("unroll") for (int m = 0; m < 4; ++m) _Pragma("unroll") for (int n = 0; n < 2; ++n) _Pragma("unroll") for (int k = 0; k < 2; ++k) \
;         acc[ai][bj][m][n] = __builtin_amdgcn_mfma_f32_16x16x32_bf16(Bt[n][k], At[m][k], acc[ai][bj][m][n], 0, 0, 0); __builtin_amdgcn_s_setprio(0); } while (0)
; #define PG8_WAIT_V(n) asm volatile("s_waitcnt vmcnt(" #n ")" ::: "memory")
; #define PG8_WAIT_L(n) asm volatile("s_waitcnt lgkmcnt(" #n ")" ::: "memory")
; #define PG8_BAR __builtin_amdgcn_s_barrier()
; #define PG8_SCHED __builtin_amdgcn_sched_barrier(0)
; template <class Epi, class Sched, bool ALIGN_EPI = false, bool SP2 = false>
; __device__ __forceinline__ void gemm_phase(PG8_LAS unsigned char* lds, const Gemm g, const Sched& S, const Epi& E) {
;     ...
;             PG8_WAIT_V(8); PG8_WAIT_L(0); PG8_BAR; PG8_MMA(1, 0, At, B0); PG8_MMA(1, 1, At, B1); PG8_BAR; PG8_SCHED;
;             PG8_LDB(B0, 1, 0); PG8_LDB(B1, 1, 1); PG8_SCHED; PG8_LDA(At, 1, 0); PG8_STAGE(PG8_SA(0, 1), a2 + hstep, voffA);
;             PG8_WAIT_V(8); PG8_WAIT_L(0); PG8_BAR; PG8_MMA(0, 0, At, B0); PG8_MMA(0, 1, At, B1); PG8_BAR; PG8_SCHED;
	s_setprio 1
	s_waitcnt lgkmcnt(0)
	v_mfma_f32_16x16x32_bf16 v[60:63], v[128:131], v[160:163], v[60:63]
	v_mfma_f32_16x16x32_bf16 v[56:59], v[136:139], v[160:163], v[56:59]
	v_mfma_f32_16x16x32_bf16 v[52:55], v[128:131], v[168:171], v[52:55]
	v_mfma_f32_16x16x32_bf16 v[48:51], v[136:139], v[168:171], v[48:51]
	v_mfma_f32_16x16x32_bf16 v[44:47], v[128:131], v[176:179], v[44:47]
	v_mfma_f32_16x16x32_bf16 v[40:43], v[136:139], v[176:179], v[40:43]
	v_mfma_f32_16x16x32_bf16 v[36:39], v[128:131], v[184:187], v[36:39]
	v_mfma_f32_16x16x32_bf16 v[32:35], v[136:139], v[184:187], v[32:35]
	v_mfma_f32_16x16x32_bf16 v[60:63], v[132:135], v[164:167], v[60:63]
	v_mfma_f32_16x16x32_bf16 v[56:59], v[140:143], v[164:167], v[56:59]
	v_mfma_f32_16x16x32_bf16 v[52:55], v[132:135], v[172:175], v[52:55]
	v_mfma_f32_16x16x32_bf16 v[48:51], v[140:143], v[172:175], v[48:51]
	v_mfma_f32_16x16x32_bf16 v[44:47], v[132:135], v[180:183], v[44:47]
	v_mfma_f32_16x16x32_bf16 v[40:43], v[140:143], v[180:183], v[40:43]
	v_mfma_f32_16x16x32_bf16 v[36:39], v[132:135], v[188:191], v[36:39]
	v_mfma_f32_16x16x32_bf16 v[32:35], v[140:143], v[188:191], v[32:35]
	v_mfma_f32_16x16x32_bf16 v[28:31], v[144:147], v[160:163], v[28:31]
	v_mfma_f32_16x16x32_bf16 v[24:27], v[152:155], v[160:163], v[24:27]
	v_mfma_f32_16x16x32_bf16 v[20:23], v[144:147], v[168:171], v[20:23]
	v_mfma_f32_16x16x32_bf16 v[16:19], v[152:155], v[168:171], v[16:19]
	v_mfma_f32_16x16x32_bf16 v[12:15], v[144:147], v[176:179], v[12:15]
	v_mfma_f32_16x16x32_bf16 v[8:11], v[152:155], v[176:179], v[8:11]
	v_mfma_f32_16x16x32_bf16 v[4:7], v[144:147], v[184:187], v[4:7]
	v_mfma_f32_16x16x32_bf16 v[0:3], v[152:155], v[184:187], v[0:3]
	v_mfma_f32_16x16x32_bf16 v[28:31], v[148:151], v[164:167], v[28:31]
	v_mfma_f32_16x16x32_bf16 v[24:27], v[156:159], v[164:167], v[24:27]
	v_mfma_f32_16x16x32_bf16 v[20:23], v[148:151], v[172:175], v[20:23]
	v_mfma_f32_16x16x32_bf16 v[16:19], v[156:159], v[172:175], v[16:19]
	v_mfma_f32_16x16x32_bf16 v[12:15], v[148:151], v[180:183], v[12:15]
	v_mfma_f32_16x16x32_bf16 v[8:11], v[156:159], v[180:183], v[8:11]
	v_mfma_f32_16x16x32_bf16 v[4:7], v[148:151], v[188:191], v[4:7]
	v_mfma_f32_16x16x32_bf16 v[0:3], v[156:159], v[188:191], v[0:3]
	s_setprio 0
	s_barrier
	s_add_i32 s77, 0, 0x18000
	s_add_i32 s78, 0, 0x1c000
	v_add_u32_e32 v140, s77, v246
	v_add_u32_e32 v156, s77, v246
	v_add_u32_e32 v156, 0x1000, v156
	ds_read_b128 v[128:131], v140
	ds_read_b128 v[132:135], v140 offset:1024
	ds_read_b128 v[136:139], v140 offset:2048
	ds_read_b128 v[140:143], v140 offset:3072
	ds_read_b128 v[144:147], v156
	ds_read_b128 v[148:151], v156 offset:1024
	ds_read_b128 v[152:155], v156 offset:2048
	ds_read_b128 v[156:159], v156 offset:3072
	s_add_u32 s10, s52, 0x40000
	s_addc_u32 s11, s53, 0
	s_mov_b32 m0, s59
	v_lshl_add_u64 v[216:217], s[10:11], 0, v[200:201]
	ds_read_b128 v[160:163], v249 offset:32768
	ds_read_b128 v[164:167], v249 offset:33792
	ds_read_b128 v[168:171], v249 offset:34816
	ds_read_b128 v[172:175], v249 offset:35840
	ds_read_b128 v[176:179], v249 offset:36864
	ds_read_b128 v[180:183], v249 offset:37888
	ds_read_b128 v[184:187], v249 offset:38912
	ds_read_b128 v[188:191], v249 offset:39936
	global_load_lds_dwordx4 v[216:217], off
	v_lshl_add_u64 v[216:217], s[10:11], 0, v[196:197]
	s_mov_b32 m0, s60
	s_nop 0
	global_load_lds_dwordx4 v[216:217], off
	s_waitcnt vmcnt(8)
	s_waitcnt lgkmcnt(0)
	s_barrier
	s_setprio 1
	s_waitcnt lgkmcnt(0)
	v_mfma_f32_16x16x32_bf16 v[124:127], v[128:131], v[160:163], v[124:127]
	v_mfma_f32_16x16x32_bf16 v[120:123], v[136:139], v[160:163], v[120:123]
	v_mfma_f32_16x16x32_bf16 v[116:119], v[128:131], v[168:171], v[116:119]
	v_mfma_f32_16x16x32_bf16 v[112:115], v[136:139], v[168:171], v[112:115]
	v_mfma_f32_16x16x32_bf16 v[108:111], v[128:131], v[176:179], v[108:111]
	v_mfma_f32_16x16x32_bf16 v[104:107], v[136:139], v[176:179], v[104:107]
	v_mfma_f32_16x16x32_bf16 v[100:103], v[128:131], v[184:187], v[100:103]
	v_mfma_f32_16x16x32_bf16 v[96:99], v[136:139], v[184:187], v[96:99]
	v_mfma_f32_16x16x32_bf16 v[124:127], v[132:135], v[164:167], v[124:127]
	v_mfma_f32_16x16x32_bf16 v[120:123], v[140:143], v[164:167], v[120:123]
	v_mfma_f32_16x16x32_bf16 v[116:119], v[132:135], v[172:175], v[116:119]
	v_mfma_f32_16x16x32_bf16 v[112:115], v[140:143], v[172:175], v[112:115]
	v_mfma_f32_16x16x32_bf16 v[108:111], v[132:135], v[180:183], v[108:111]
	v_mfma_f32_16x16x32_bf16 v[104:107], v[140:143], v[180:183], v[104:107]
	v_mfma_f32_16x16x32_bf16 v[100:103], v[132:135], v[188:191], v[100:103]
	v_mfma_f32_16x16x32_bf16 v[96:99], v[140:143], v[188:191], v[96:99]
	v_mfma_f32_16x16x32_bf16 v[92:95], v[144:147], v[160:163], v[92:95]
	v_mfma_f32_16x16x32_bf16 v[88:91], v[152:155], v[160:163], v[88:91]
	v_mfma_f32_16x16x32_bf16 v[84:87], v[144:147], v[168:171], v[84:87]
	v_mfma_f32_16x16x32_bf16 v[80:83], v[152:155], v[168:171], v[80:83]
	v_mfma_f32_16x16x32_bf16 v[76:79], v[144:147], v[176:179], v[76:79]
	v_mfma_f32_16x16x32_bf16 v[72:75], v[152:155], v[176:179], v[72:75]
	v_mfma_f32_16x16x32_bf16 v[68:71], v[144:147], v[184:187], v[68:71]
	v_mfma_f32_16x16x32_bf16 v[64:67], v[152:155], v[184:187], v[64:67]
	v_mfma_f32_16x16x32_bf16 v[92:95], v[148:151], v[164:167], v[92:95]
	v_mfma_f32_16x16x32_bf16 v[88:91], v[156:159], v[164:167], v[88:91]
	v_mfma_f32_16x16x32_bf16 v[84:87], v[148:151], v[172:175], v[84:87]
	v_mfma_f32_16x16x32_bf16 v[80:83], v[156:159], v[172:175], v[80:83]
	v_mfma_f32_16x16x32_bf16 v[76:79], v[148:151], v[180:183], v[76:79]
	v_mfma_f32_16x16x32_bf16 v[72:75], v[156:159], v[180:183], v[72:75]
	v_mfma_f32_16x16x32_bf16 v[68:71], v[148:151], v[188:191], v[68:71]
	v_mfma_f32_16x16x32_bf16 v[64:67], v[156:159], v[188:191], v[64:67]
	s_setprio 0
	s_barrier
; #define PG8_STAGE(bufoff, gbase, voff) do { _Pragma("unroll") for (int _i = 0; _i < 2; ++_i) \
;         __builtin_amdgcn_global_load_lds((const unsigned*)((const char*)(gbase) + (voff)[_i]), (PG8_LAS unsigned*)(lds + (bufoff) + ldsw + _i * 8192), 16, 0, 0); } while (0)
; #define PG8_LDA(dst, b, h) do { _Pragma("unroll") for (int m = 0; m < 4; ++m) _Pragma("unroll") for (int k = 0; k < 2; ++k) dst[m][k] = *(const PG8_LAS bf16x8*)(lds + PG8_SA(b, h) + aoff + m * 2048 + k * 1024); } while (0)
; #define PG8_MMA(ai, bj, At, Bt) do { __builtin_amdgcn_s_setprio(1); _Pragma("unroll") for (int m = 0; m < 4; ++m) _Pragma("unroll") for (int n = 0; n < 2; ++n) _Pragma("unroll") for (int k = 0; k < 2; ++k) \
;         acc[ai][bj][m][n] = __builtin_amdgcn_mfma_f32_16x16x32_bf16(Bt[n][k], At[m][k], acc[ai][bj][m][n], 0, 0, 0); __builtin_amdgcn_s_setprio(0); } while (0)
; #define PG8_WAIT_V(n) asm volatile("s_waitcnt vmcnt(" #n ")" ::: "memory")
; #define PG8_WAIT_L(n) asm volatile("s_waitcnt lgkmcnt(" #n ")" ::: "memory")
; #define PG8_BAR __builtin_amdgcn_s_barrier()
; #define PG8_SCHED __builtin_amdgcn_sched_barrier(0)
; template <class Epi, class Sched, bool ALIGN_EPI = false, bool SP2 = false>
; __device__ __forceinline__ void gemm_phase(PG8_LAS unsigned char* lds, const Gemm g, const Sched& S, const Epi& E) {
;     ...
;             PG8_LDA(At, 1, 1); PG8_STAGE(PG8_SB(1, 0), b3, voffB); PG8_STAGE(PG8_SB(1, 1), b3 + hstep, voffB); PG8_STAGE(PG8_SA(1, 0), a3, voffA);
;             PG8_WAIT_V(8); PG8_WAIT_L(0); PG8_BAR; PG8_MMA(1, 0, At, B0); PG8_MMA(1, 1, At, B1); PG8_BAR; PG8_SCHED;
;     ...
;         if constexpr (ALIGN_EPI) { if (wr == 0) PG8_BAR; }
	s_add_i32 s10, s77, s14
	v_lshl_add_u64 v[208:209], v[208:209], 0, s[36:37]
	s_mov_b32 m0, s10
	ds_read_b128 v[160:163], v249 offset:49152
	ds_read_b128 v[164:167], v249 offset:50176
	ds_read_b128 v[168:171], v249 offset:51200
	ds_read_b128 v[172:175], v249 offset:52224
	ds_read_b128 v[176:179], v249 offset:53248
	ds_read_b128 v[180:183], v249 offset:54272
	ds_read_b128 v[184:187], v249 offset:55296
	ds_read_b128 v[188:191], v249 offset:56320
	global_load_lds_dwordx4 v[208:209], off
	s_add_i32 m0, s10, 0x2000
	s_add_u32 s10, s50, 0x40080
	v_lshl_add_u64 v[208:209], v[210:211], 0, s[36:37]
	s_addc_u32 s11, s51, 0
	s_add_i32 s50, s78, s14
	global_load_lds_dwordx4 v[208:209], off
	v_lshl_add_u64 v[208:209], s[10:11], 0, v[198:199]
	s_mov_b32 m0, s50
	s_nop 0
	global_load_lds_dwordx4 v[208:209], off
	v_lshl_add_u64 v[208:209], s[10:11], 0, v[194:195]
	s_add_i32 m0, s50, 0x2000
	s_nop 0
	global_load_lds_dwordx4 v[208:209], off
	v_lshl_add_u64 v[208:209], v[212:213], 0, s[36:37]
	s_mov_b32 m0, s65
	s_nop 0
	global_load_lds_dwordx4 v[208:209], off
	v_lshl_add_u64 v[208:209], v[214:215], 0, s[36:37]
	s_mov_b32 m0, s66
	s_nop 0
	global_load_lds_dwordx4 v[208:209], off
	s_waitcnt vmcnt(8)
	s_waitcnt lgkmcnt(0)
	s_barrier
	s_setprio 1
	s_waitcnt lgkmcnt(0)
	v_mfma_f32_16x16x32_bf16 v[60:63], v[128:131], v[160:163], v[60:63]
	v_mfma_f32_16x16x32_bf16 v[56:59], v[136:139], v[160:163], v[56:59]
	v_mfma_f32_16x16x32_bf16 v[52:55], v[128:131], v[168:171], v[52:55]
	v_mfma_f32_16x16x32_bf16 v[48:51], v[136:139], v[168:171], v[48:51]
	v_mfma_f32_16x16x32_bf16 v[44:47], v[128:131], v[176:179], v[44:47]
	v_mfma_f32_16x16x32_bf16 v[40:43], v[136:139], v[176:179], v[40:43]
	v_mfma_f32_16x16x32_bf16 v[36:39], v[128:131], v[184:187], v[36:39]
	v_mfma_f32_16x16x32_bf16 v[32:35], v[136:139], v[184:187], v[32:35]
	v_mfma_f32_16x16x32_bf16 v[60:63], v[132:135], v[164:167], v[60:63]
	v_mfma_f32_16x16x32_bf16 v[56:59], v[140:143], v[164:167], v[56:59]
	v_mfma_f32_16x16x32_bf16 v[52:55], v[132:135], v[172:175], v[52:55]
	v_mfma_f32_16x16x32_bf16 v[48:51], v[140:143], v[172:175], v[48:51]
	v_mfma_f32_16x16x32_bf16 v[44:47], v[132:135], v[180:183], v[44:47]
	v_mfma_f32_16x16x32_bf16 v[40:43], v[140:143], v[180:183], v[40:43]
	v_mfma_f32_16x16x32_bf16 v[36:39], v[132:135], v[188:191], v[36:39]
	v_mfma_f32_16x16x32_bf16 v[32:35], v[140:143], v[188:191], v[32:35]
	v_mfma_f32_16x16x32_bf16 v[28:31], v[144:147], v[160:163], v[28:31]
	v_mfma_f32_16x16x32_bf16 v[24:27], v[152:155], v[160:163], v[24:27]
	v_mfma_f32_16x16x32_bf16 v[20:23], v[144:147], v[168:171], v[20:23]
	v_mfma_f32_16x16x32_bf16 v[16:19], v[152:155], v[168:171], v[16:19]
	v_mfma_f32_16x16x32_bf16 v[12:15], v[144:147], v[176:179], v[12:15]
	v_mfma_f32_16x16x32_bf16 v[8:11], v[152:155], v[176:179], v[8:11]
	v_mfma_f32_16x16x32_bf16 v[4:7], v[144:147], v[184:187], v[4:7]
	v_mfma_f32_16x16x32_bf16 v[0:3], v[152:155], v[184:187], v[0:3]
	v_mfma_f32_16x16x32_bf16 v[28:31], v[148:151], v[164:167], v[28:31]
	v_mfma_f32_16x16x32_bf16 v[24:27], v[156:159], v[164:167], v[24:27]
	v_mfma_f32_16x16x32_bf16 v[20:23], v[148:151], v[172:175], v[20:23]
	v_mfma_f32_16x16x32_bf16 v[16:19], v[156:159], v[172:175], v[16:19]
	v_mfma_f32_16x16x32_bf16 v[12:15], v[148:151], v[180:183], v[12:15]
	v_mfma_f32_16x16x32_bf16 v[8:11], v[156:159], v[180:183], v[8:11]
	v_mfma_f32_16x16x32_bf16 v[4:7], v[148:151], v[188:191], v[4:7]
	v_mfma_f32_16x16x32_bf16 v[0:3], v[156:159], v[188:191], v[0:3]
	s_setprio 0
	s_barrier
	s_add_i32 s76, s76, 2
	s_add_u32 s34, s34, 0x100
	s_addc_u32 s35, s35, 0
	s_add_u32 s19, s19, 0x100
	s_addc_u32 s75, s75, 0
	s_cmp_gt_u32 s76, 5
	s_cbranch_scc0 .LBB0_488
	s_and_b64 vcc, exec, s[24:25]
	s_cbranch_vccz .LBB0_491
	s_barrier

; #define PG8_STAGE(bufoff, gbase, voff) do { _Pragma("unroll") for (int _i = 0; _i < 2; ++_i) \
;         __builtin_amdgcn_global_load_lds((const unsigned*)((const char*)(gbase) + (voff)[_i]), (PG8_LAS unsigned*)(lds + (bufoff) + ldsw + _i * 8192), 16, 0, 0); } while (0)
; #define PG8_LDA(dst, b, h) do { _Pragma("unroll") for (int m = 0; m < 4; ++m) _Pragma("unroll") for (int k = 0; k < 2; ++k) dst[m][k] = *(const PG8_LAS bf16x8*)(lds + PG8_SA(b, h) + aoff + m * 2048 + k * 1024); } while (0)
; #define PG8_LDB(dst, b, h) do { _Pragma("unroll") for (int n = 0; n < 2; ++n) _Pragma("unroll") for (int k = 0; k < 2; ++k) dst[n][k] = *(const PG8_LAS bf16x8*)(lds + PG8_SB(b, h) + boff + n * 2048 + k * 1024); } while (0)
; #define PG8_MMA(ai, bj, At, Bt) do { __builtin_amdgcn_s_setprio(1); _Pragma("unroll") for (int m = 0; m < 4; ++m) _Pragma("unroll") for (int n = 0; n < 2; ++n) _Pragma("unroll") for (int k = 0; k < 2; ++k) \
;         acc[ai][bj][m][n] = __builtin_amdgcn_mfma_f32_16x16x32_bf16(Bt[n][k], At[m][k], acc[ai][bj][m][n], 0, 0, 0); __builtin_amdgcn_s_setprio(0); } while (0)
; #define PG8_WAIT_V(n) asm volatile("s_waitcnt vmcnt(" #n ")" ::: "memory")
; #define PG8_WAIT_L(n) asm volatile("s_waitcnt lgkmcnt(" #n ")" ::: "memory")
; #define PG8_BAR __builtin_amdgcn_s_barrier()
; #define PG8_SCHED __builtin_amdgcn_sched_barrier(0)
; template <class Epi, class Sched, bool ALIGN_EPI = false, bool SP2 = false>
; __device__ __forceinline__ void gemm_phase(PG8_LAS unsigned char* lds, const Gemm g, const Sched& S, const Epi& E) {
;     ...
;             const bool last = (t == nt - 2);
;             const char* a1 = cA + (size_t)(t + 1) * kstep;
;             const char* a2 = last ? nA : cA + (size_t)(t + 2) * kstep; const char* b2 = last ? nB : cB + (size_t)(t + 2) * kstep;
;             const char* a3 = a2 + kstep; const char* b3 = b2 + kstep;
;             if (last && has_next) S.a_ready(nxt);
;             if constexpr (SP2) {
;             PG8_LDB(B0, 0, 0); PG8_LDB(B1, 0, 1); PG8_SCHED; PG8_LDA(At, 0, 0); PG8_STAGE(PG8_SA(1, 1), a1 + hstep, voffA);
;             PG8_WAIT_V(8); PG8_WAIT_L(0); PG8_BAR; PG8_MMA(0, 0, At, B0); PG8_MMA(0, 1, At, B1); PG8_BAR; PG8_SCHED;
;             PG8_LDA(At, 0, 1); PG8_STAGE(PG8_SB(0, 0), b2, voffB); PG8_STAGE(PG8_SB(0, 1), b2 + hstep, voffB); PG8_STAGE(PG8_SA(0, 0), a2, voffA);
.LBB0_577:
	s_add_u32 s10, s44, 0xfffc0080
	s_addc_u32 s11, s45, -1
	s_add_i32 s64, 0, 0x10000
	s_cmp_eq_u32 s63, 12
	s_cselect_b32 s49, s29, s11
	s_cselect_b32 s48, s43, s10
	v_add_u32_e32 v146, s64, v149
	s_cselect_b32 s47, s27, s62
	s_cselect_b32 s46, s60, s61
	s_add_i32 s65, 0, 0x14000
	ds_read_b128 v[128:131], v146
	ds_read_b128 v[154:157], v146 offset:1024
	ds_read_b128 v[158:161], v146 offset:2048
	ds_read_b128 v[162:165], v146 offset:3072
	v_add_u32_e32 v146, s65, v149
	ds_read_b128 v[166:169], v146
	ds_read_b128 v[170:173], v146 offset:1024
	ds_read_b128 v[174:177], v146 offset:2048
	ds_read_b128 v[178:181], v146 offset:3072
	v_lshl_add_u64 v[190:191], s[44:45], 0, v[142:143]
	s_add_i32 m0, s51, 0xc000
	ds_read_b128 v[182:185], v153
	ds_read_b128 v[186:189], v153 offset:1024
	ds_read_b128 v[194:197], v153 offset:2048
	ds_read_b128 v[198:201], v153 offset:3072
	ds_read_b128 v[202:205], v153 offset:4096
	ds_read_b128 v[206:209], v153 offset:5120
	ds_read_b128 v[210:213], v153 offset:6144
	ds_read_b128 v[214:217], v153 offset:7168
	global_load_lds_dwordx4 v[190:191], off
	v_lshl_add_u64 v[190:191], s[44:45], 0, v[144:145]
	s_add_i32 m0, s51, 0xe000
	s_nop 0
	global_load_lds_dwordx4 v[190:191], off
	s_waitcnt vmcnt(8)
	s_waitcnt lgkmcnt(0)
	s_barrier
	s_setprio 1
	s_waitcnt lgkmcnt(0)
	v_mfma_f32_16x16x32_bf16 v[124:127], v[128:131], v[182:185], v[124:127]
	v_mfma_f32_16x16x32_bf16 v[116:119], v[158:161], v[182:185], v[116:119]
	v_mfma_f32_16x16x32_bf16 v[108:111], v[128:131], v[194:197], v[108:111]
	v_mfma_f32_16x16x32_bf16 v[100:103], v[158:161], v[194:197], v[100:103]
	v_mfma_f32_16x16x32_bf16 v[92:95], v[128:131], v[202:205], v[92:95]
	v_mfma_f32_16x16x32_bf16 v[84:87], v[158:161], v[202:205], v[84:87]
	v_mfma_f32_16x16x32_bf16 v[76:79], v[128:131], v[210:213], v[76:79]
	v_mfma_f32_16x16x32_bf16 v[68:71], v[158:161], v[210:213], v[68:71]
	v_mfma_f32_16x16x32_bf16 v[124:127], v[154:157], v[186:189], v[124:127]
	v_mfma_f32_16x16x32_bf16 v[116:119], v[162:165], v[186:189], v[116:119]
	v_mfma_f32_16x16x32_bf16 v[108:111], v[154:157], v[198:201], v[108:111]
	v_mfma_f32_16x16x32_bf16 v[100:103], v[162:165], v[198:201], v[100:103]
	v_mfma_f32_16x16x32_bf16 v[92:95], v[154:157], v[206:209], v[92:95]
	v_mfma_f32_16x16x32_bf16 v[84:87], v[162:165], v[206:209], v[84:87]
	v_mfma_f32_16x16x32_bf16 v[76:79], v[154:157], v[214:217], v[76:79]
	v_mfma_f32_16x16x32_bf16 v[68:71], v[162:165], v[214:217], v[68:71]
	v_mfma_f32_16x16x32_bf16 v[120:123], v[166:169], v[182:185], v[120:123]
	v_mfma_f32_16x16x32_bf16 v[112:115], v[174:177], v[182:185], v[112:115]
	v_mfma_f32_16x16x32_bf16 v[104:107], v[166:169], v[194:197], v[104:107]
	v_mfma_f32_16x16x32_bf16 v[96:99], v[174:177], v[194:197], v[96:99]
	v_mfma_f32_16x16x32_bf16 v[88:91], v[166:169], v[202:205], v[88:91]
	v_mfma_f32_16x16x32_bf16 v[80:83], v[174:177], v[202:205], v[80:83]
	v_mfma_f32_16x16x32_bf16 v[72:75], v[166:169], v[210:213], v[72:75]
	v_mfma_f32_16x16x32_bf16 v[64:67], v[174:177], v[210:213], v[64:67]
	v_mfma_f32_16x16x32_bf16 v[120:123], v[170:173], v[186:189], v[120:123]
	v_mfma_f32_16x16x32_bf16 v[112:115], v[178:181], v[186:189], v[112:115]
	v_mfma_f32_16x16x32_bf16 v[104:107], v[170:173], v[198:201], v[104:107]
	v_mfma_f32_16x16x32_bf16 v[96:99], v[178:181], v[198:201], v[96:99]
	v_mfma_f32_16x16x32_bf16 v[88:91], v[170:173], v[206:209], v[88:91]
	v_mfma_f32_16x16x32_bf16 v[80:83], v[178:181], v[206:209], v[80:83]
	v_mfma_f32_16x16x32_bf16 v[72:75], v[170:173], v[214:217], v[72:75]
	v_mfma_f32_16x16x32_bf16 v[64:67], v[178:181], v[214:217], v[64:67]
	s_setprio 0
	s_barrier
	s_add_i32 s10, s64, s19
	v_lshl_add_u64 v[190:191], s[46:47], 0, v[136:137]
	s_mov_b32 m0, s10
	ds_read_b128 v[182:185], v153 offset:16384
	ds_read_b128 v[186:189], v153 offset:17408
	ds_read_b128 v[194:197], v153 offset:18432
	ds_read_b128 v[198:201], v153 offset:19456
	ds_read_b128 v[202:205], v153 offset:20480
	ds_read_b128 v[206:209], v153 offset:21504
	ds_read_b128 v[210:213], v153 offset:22528
	ds_read_b128 v[214:217], v153 offset:23552
	global_load_lds_dwordx4 v[190:191], off
	s_add_i32 m0, s10, 0x2000
	s_add_u32 s10, s46, 0x40000
	v_lshl_add_u64 v[218:219], s[46:47], 0, v[132:133]
	s_addc_u32 s11, s47, 0
	s_add_i32 s64, s65, s19
	global_load_lds_dwordx4 v[218:219], off
	v_lshl_add_u64 v[220:221], s[10:11], 0, v[136:137]
	s_mov_b32 m0, s64
	v_lshl_add_u64 v[222:223], s[48:49], 0, v[134:135]
	global_load_lds_dwordx4 v[220:221], off
	v_lshl_add_u64 v[220:221], s[10:11], 0, v[132:133]
	s_add_i32 m0, s64, 0x2000
	s_nop 0
	global_load_lds_dwordx4 v[220:221], off
	v_lshl_add_u64 v[220:221], s[48:49], 0, v[138:139]
	s_mov_b32 m0, s51
	s_nop 0
	global_load_lds_dwordx4 v[220:221], off
	s_mov_b32 m0, s52
	s_nop 0
	global_load_lds_dwordx4 v[222:223], off
	s_waitcnt vmcnt(8)
	s_waitcnt lgkmcnt(0)
	s_barrier
; #define PG8_STAGE(bufoff, gbase, voff) do { _Pragma("unroll") for (int _i = 0; _i < 2; ++_i) \
;         __builtin_amdgcn_global_load_lds((const unsigned*)((const char*)(gbase) + (voff)[_i]), (PG8_LAS unsigned*)(lds + (bufoff) + ldsw + _i * 8192), 16, 0, 0); } while (0)
; #define PG8_LDA(dst, b, h) do { _Pragma("unroll") for (int m = 0; m < 4; ++m) _Pragma("unroll") for (int k = 0; k < 2; ++k) dst[m][k] = *(const PG8_LAS bf16x8*)(lds + PG8_SA(b, h) + aoff + m * 2048 + k * 1024); } while (0)
; #define PG8_LDB(dst, b, h) do { _Pragma("unroll") for (int n = 0; n < 2; ++n) _Pragma("unroll") for (int k = 0; k < 2; ++k) dst[n][k] = *(const PG8_LAS bf16x8*)(lds + PG8_SB(b, h) + boff + n * 2048 + k * 1024); } while (0)
; #define PG8_MMA(ai, bj, At, Bt) do { __builtin_amdgcn_s_setprio(1); _Pragma("unroll") for (int m = 0; m < 4; ++m) _Pragma("unroll") for (int n = 0; n < 2; ++n) _Pragma("unroll") for (int k = 0; k < 2; ++k) \
;         acc[ai][bj][m][n] = __builtin_amdgcn_mfma_f32_16x16x32_bf16(Bt[n][k], At[m][k], acc[ai][bj][m][n], 0, 0, 0); __builtin_amdgcn_s_setprio(0); } while (0)
; #define PG8_WAIT_V(n) asm volatile("s_waitcnt vmcnt(" #n ")" ::: "memory")
; #define PG8_WAIT_L(n) asm volatile("s_waitcnt lgkmcnt(" #n ")" ::: "memory")
; #define PG8_BAR __builtin_amdgcn_s_barrier()
; #define PG8_SCHED __builtin_amdgcn_sched_barrier(0)
; template <class Epi, class Sched, bool ALIGN_EPI = false, bool SP2 = false>
; __device__ __forceinline__ void gemm_phase(PG8_LAS unsigned char* lds, const Gemm g, const Sched& S, const Epi& E) {
;     ...
;             PG8_WAIT_V(8); PG8_WAIT_L(0); PG8_BAR; PG8_MMA(1, 0, At, B0); PG8_MMA(1, 1, At, B1); PG8_BAR; PG8_SCHED;
;             PG8_LDB(B0, 1, 0); PG8_LDB(B1, 1, 1); PG8_SCHED; PG8_LDA(At, 1, 0); PG8_STAGE(PG8_SA(0, 1), a2 + hstep, voffA);
;             PG8_WAIT_V(8); PG8_WAIT_L(0); PG8_BAR; PG8_MMA(0, 0, At, B0); PG8_MMA(0, 1, At, B1); PG8_BAR; PG8_SCHED;
	s_setprio 1
	s_waitcnt lgkmcnt(0)
	v_mfma_f32_16x16x32_bf16 v[60:63], v[128:131], v[182:185], v[60:63]
	v_mfma_f32_16x16x32_bf16 v[52:55], v[158:161], v[182:185], v[52:55]
	v_mfma_f32_16x16x32_bf16 v[44:47], v[128:131], v[194:197], v[44:47]
	v_mfma_f32_16x16x32_bf16 v[36:39], v[158:161], v[194:197], v[36:39]
	v_mfma_f32_16x16x32_bf16 v[28:31], v[128:131], v[202:205], v[28:31]
	v_mfma_f32_16x16x32_bf16 v[20:23], v[158:161], v[202:205], v[20:23]
	v_mfma_f32_16x16x32_bf16 v[12:15], v[128:131], v[210:213], v[12:15]
	v_mfma_f32_16x16x32_bf16 v[4:7], v[158:161], v[210:213], v[4:7]
	v_mfma_f32_16x16x32_bf16 v[60:63], v[154:157], v[186:189], v[60:63]
	v_mfma_f32_16x16x32_bf16 v[52:55], v[162:165], v[186:189], v[52:55]
	v_mfma_f32_16x16x32_bf16 v[44:47], v[154:157], v[198:201], v[44:47]
	v_mfma_f32_16x16x32_bf16 v[36:39], v[162:165], v[198:201], v[36:39]
	v_mfma_f32_16x16x32_bf16 v[28:31], v[154:157], v[206:209], v[28:31]
	v_mfma_f32_16x16x32_bf16 v[20:23], v[162:165], v[206:209], v[20:23]
	v_mfma_f32_16x16x32_bf16 v[12:15], v[154:157], v[214:217], v[12:15]
	v_mfma_f32_16x16x32_bf16 v[4:7], v[162:165], v[214:217], v[4:7]
	v_mfma_f32_16x16x32_bf16 v[56:59], v[166:169], v[182:185], v[56:59]
	v_mfma_f32_16x16x32_bf16 v[48:51], v[174:177], v[182:185], v[48:51]
	v_mfma_f32_16x16x32_bf16 v[40:43], v[166:169], v[194:197], v[40:43]
	v_mfma_f32_16x16x32_bf16 v[32:35], v[174:177], v[194:197], v[32:35]
	v_mfma_f32_16x16x32_bf16 v[24:27], v[166:169], v[202:205], v[24:27]
	v_mfma_f32_16x16x32_bf16 v[16:19], v[174:177], v[202:205], v[16:19]
	v_mfma_f32_16x16x32_bf16 v[8:11], v[166:169], v[210:213], v[8:11]
	v_mfma_f32_16x16x32_bf16 v[0:3], v[174:177], v[210:213], v[0:3]
	v_mfma_f32_16x16x32_bf16 v[56:59], v[170:173], v[186:189], v[56:59]
	v_mfma_f32_16x16x32_bf16 v[48:51], v[178:181], v[186:189], v[48:51]
	v_mfma_f32_16x16x32_bf16 v[40:43], v[170:173], v[198:201], v[40:43]
	v_mfma_f32_16x16x32_bf16 v[32:35], v[178:181], v[198:201], v[32:35]
	v_mfma_f32_16x16x32_bf16 v[24:27], v[170:173], v[206:209], v[24:27]
	v_mfma_f32_16x16x32_bf16 v[16:19], v[178:181], v[206:209], v[16:19]
	v_mfma_f32_16x16x32_bf16 v[8:11], v[170:173], v[214:217], v[8:11]
	v_mfma_f32_16x16x32_bf16 v[0:3], v[178:181], v[214:217], v[0:3]
	s_setprio 0
	s_barrier
	s_add_i32 s64, 0, 0x18000
	v_add_u32_e32 v146, s64, v149
	s_add_i32 s65, 0, 0x1c000
	ds_read_b128 v[128:131], v146
	ds_read_b128 v[154:157], v146 offset:1024
	ds_read_b128 v[158:161], v146 offset:2048
	ds_read_b128 v[162:165], v146 offset:3072
	v_add_u32_e32 v146, s65, v149
	ds_read_b128 v[166:169], v146
	ds_read_b128 v[170:173], v146 offset:1024
	ds_read_b128 v[174:177], v146 offset:2048
	ds_read_b128 v[178:181], v146 offset:3072
	s_add_u32 s10, s48, 0x40000
	s_addc_u32 s11, s49, 0
	s_mov_b32 m0, s53
	v_lshl_add_u64 v[224:225], s[10:11], 0, v[138:139]
	ds_read_b128 v[182:185], v153 offset:32768
	ds_read_b128 v[186:189], v153 offset:33792
	ds_read_b128 v[194:197], v153 offset:34816
	ds_read_b128 v[198:201], v153 offset:35840
	ds_read_b128 v[202:205], v153 offset:36864
	ds_read_b128 v[206:209], v153 offset:37888
	ds_read_b128 v[210:213], v153 offset:38912
	ds_read_b128 v[214:217], v153 offset:39936
	global_load_lds_dwordx4 v[224:225], off
	v_lshl_add_u64 v[224:225], s[10:11], 0, v[134:135]
	s_mov_b32 m0, s54
	s_nop 0
	global_load_lds_dwordx4 v[224:225], off
	s_waitcnt vmcnt(8)
	s_waitcnt lgkmcnt(0)
	s_barrier
	s_setprio 1
	s_waitcnt lgkmcnt(0)
	v_mfma_f32_16x16x32_bf16 v[124:127], v[128:131], v[182:185], v[124:127]
	v_mfma_f32_16x16x32_bf16 v[116:119], v[158:161], v[182:185], v[116:119]
	v_mfma_f32_16x16x32_bf16 v[108:111], v[128:131], v[194:197], v[108:111]
	v_mfma_f32_16x16x32_bf16 v[100:103], v[158:161], v[194:197], v[100:103]
	v_mfma_f32_16x16x32_bf16 v[92:95], v[128:131], v[202:205], v[92:95]
	v_mfma_f32_16x16x32_bf16 v[84:87], v[158:161], v[202:205], v[84:87]
	v_mfma_f32_16x16x32_bf16 v[76:79], v[128:131], v[210:213], v[76:79]
	v_mfma_f32_16x16x32_bf16 v[68:71], v[158:161], v[210:213], v[68:71]
	v_mfma_f32_16x16x32_bf16 v[124:127], v[154:157], v[186:189], v[124:127]
	v_mfma_f32_16x16x32_bf16 v[116:119], v[162:165], v[186:189], v[116:119]
	v_mfma_f32_16x16x32_bf16 v[108:111], v[154:157], v[198:201], v[108:111]
	v_mfma_f32_16x16x32_bf16 v[100:103], v[162:165], v[198:201], v[100:103]
	v_mfma_f32_16x16x32_bf16 v[92:95], v[154:157], v[206:209], v[92:95]
	v_mfma_f32_16x16x32_bf16 v[84:87], v[162:165], v[206:209], v[84:87]
	v_mfma_f32_16x16x32_bf16 v[76:79], v[154:157], v[214:217], v[76:79]
	v_mfma_f32_16x16x32_bf16 v[68:71], v[162:165], v[214:217], v[68:71]
	v_mfma_f32_16x16x32_bf16 v[120:123], v[166:169], v[182:185], v[120:123]
	v_mfma_f32_16x16x32_bf16 v[112:115], v[174:177], v[182:185], v[112:115]
	v_mfma_f32_16x16x32_bf16 v[104:107], v[166:169], v[194:197], v[104:107]
	v_mfma_f32_16x16x32_bf16 v[96:99], v[174:177], v[194:197], v[96:99]
	v_mfma_f32_16x16x32_bf16 v[88:91], v[166:169], v[202:205], v[88:91]
	v_mfma_f32_16x16x32_bf16 v[80:83], v[174:177], v[202:205], v[80:83]
	v_mfma_f32_16x16x32_bf16 v[72:75], v[166:169], v[210:213], v[72:75]
	v_mfma_f32_16x16x32_bf16 v[64:67], v[174:177], v[210:213], v[64:67]
	v_mfma_f32_16x16x32_bf16 v[120:123], v[170:173], v[186:189], v[120:123]
	v_mfma_f32_16x16x32_bf16 v[112:115], v[178:181], v[186:189], v[112:115]
	v_mfma_f32_16x16x32_bf16 v[104:107], v[170:173], v[198:201], v[104:107]
	v_mfma_f32_16x16x32_bf16 v[96:99], v[178:181], v[198:201], v[96:99]
	v_mfma_f32_16x16x32_bf16 v[88:91], v[170:173], v[206:209], v[88:91]
	v_mfma_f32_16x16x32_bf16 v[80:83], v[178:181], v[206:209], v[80:83]
	v_mfma_f32_16x16x32_bf16 v[72:75], v[170:173], v[214:217], v[72:75]
	v_mfma_f32_16x16x32_bf16 v[64:67], v[178:181], v[214:217], v[64:67]
	s_setprio 0
	s_barrier
; #define PG8_STAGE(bufoff, gbase, voff) do { _Pragma("unroll") for (int _i = 0; _i < 2; ++_i) \
;         __builtin_amdgcn_global_load_lds((const unsigned*)((const char*)(gbase) + (voff)[_i]), (PG8_LAS unsigned*)(lds + (bufoff) + ldsw + _i * 8192), 16, 0, 0); } while (0)
; #define PG8_LDA(dst, b, h) do { _Pragma("unroll") for (int m = 0; m < 4; ++m) _Pragma("unroll") for (int k = 0; k < 2; ++k) dst[m][k] = *(const PG8_LAS bf16x8*)(lds + PG8_SA(b, h) + aoff + m * 2048 + k * 1024); } while (0)
; #define PG8_MMA(ai, bj, At, Bt) do { __builtin_amdgcn_s_setprio(1); _Pragma("unroll") for (int m = 0; m < 4; ++m) _Pragma("unroll") for (int n = 0; n < 2; ++n) _Pragma("unroll") for (int k = 0; k < 2; ++k) \
;         acc[ai][bj][m][n] = __builtin_amdgcn_mfma_f32_16x16x32_bf16(Bt[n][k], At[m][k], acc[ai][bj][m][n], 0, 0, 0); __builtin_amdgcn_s_setprio(0); } while (0)
; #define PG8_WAIT_V(n) asm volatile("s_waitcnt vmcnt(" #n ")" ::: "memory")
; #define PG8_WAIT_L(n) asm volatile("s_waitcnt lgkmcnt(" #n ")" ::: "memory")
; #define PG8_BAR __builtin_amdgcn_s_barrier()
; #define PG8_SCHED __builtin_amdgcn_sched_barrier(0)
; template <class Epi, class Sched, bool ALIGN_EPI = false, bool SP2 = false>
; __device__ __forceinline__ void gemm_phase(PG8_LAS unsigned char* lds, const Gemm g, const Sched& S, const Epi& E) {
;     ...
;             PG8_LDA(At, 1, 1); PG8_STAGE(PG8_SB(1, 0), b3, voffB); PG8_STAGE(PG8_SB(1, 1), b3 + hstep, voffB); PG8_STAGE(PG8_SA(1, 0), a3, voffA);
;             PG8_WAIT_V(8); PG8_WAIT_L(0); PG8_BAR; PG8_MMA(1, 0, At, B0); PG8_MMA(1, 1, At, B1); PG8_BAR; PG8_SCHED;
;     ...
;         if constexpr (ALIGN_EPI) { if (wr == 0) PG8_BAR; }
	s_add_i32 s10, s64, s19
	v_lshl_add_u64 v[190:191], v[190:191], 0, s[36:37]
	s_mov_b32 m0, s10
	ds_read_b128 v[182:185], v153 offset:49152
	ds_read_b128 v[186:189], v153 offset:50176
	ds_read_b128 v[194:197], v153 offset:51200
	ds_read_b128 v[198:201], v153 offset:52224
	ds_read_b128 v[202:205], v153 offset:53248
	ds_read_b128 v[206:209], v153 offset:54272
	ds_read_b128 v[210:213], v153 offset:55296
	ds_read_b128 v[214:217], v153 offset:56320
	global_load_lds_dwordx4 v[190:191], off
	s_add_i32 m0, s10, 0x2000
	s_add_u32 s10, s46, 0x40080
	v_lshl_add_u64 v[190:191], v[218:219], 0, s[36:37]
	s_addc_u32 s11, s47, 0
	s_add_i32 s46, s65, s19
	global_load_lds_dwordx4 v[190:191], off
	v_lshl_add_u64 v[190:191], s[10:11], 0, v[136:137]
	s_mov_b32 m0, s46
	s_nop 0
	global_load_lds_dwordx4 v[190:191], off
	v_lshl_add_u64 v[190:191], s[10:11], 0, v[132:133]
	s_add_i32 m0, s46, 0x2000
	s_nop 0
	global_load_lds_dwordx4 v[190:191], off
	v_lshl_add_u64 v[190:191], v[220:221], 0, s[36:37]
	s_mov_b32 m0, s20
	s_nop 0
	global_load_lds_dwordx4 v[190:191], off
	v_lshl_add_u64 v[190:191], v[222:223], 0, s[36:37]
	s_mov_b32 m0, s55
	s_nop 0
	global_load_lds_dwordx4 v[190:191], off
	s_waitcnt vmcnt(8)
	s_waitcnt lgkmcnt(0)
	s_barrier
	s_setprio 1
	s_waitcnt lgkmcnt(0)
	v_mfma_f32_16x16x32_bf16 v[60:63], v[128:131], v[182:185], v[60:63]
	v_mfma_f32_16x16x32_bf16 v[52:55], v[158:161], v[182:185], v[52:55]
	v_mfma_f32_16x16x32_bf16 v[44:47], v[128:131], v[194:197], v[44:47]
	v_mfma_f32_16x16x32_bf16 v[36:39], v[158:161], v[194:197], v[36:39]
	v_mfma_f32_16x16x32_bf16 v[28:31], v[128:131], v[202:205], v[28:31]
	v_mfma_f32_16x16x32_bf16 v[20:23], v[158:161], v[202:205], v[20:23]
	v_mfma_f32_16x16x32_bf16 v[12:15], v[128:131], v[210:213], v[12:15]
	v_mfma_f32_16x16x32_bf16 v[4:7], v[158:161], v[210:213], v[4:7]
	v_mfma_f32_16x16x32_bf16 v[60:63], v[154:157], v[186:189], v[60:63]
	v_mfma_f32_16x16x32_bf16 v[52:55], v[162:165], v[186:189], v[52:55]
	v_mfma_f32_16x16x32_bf16 v[44:47], v[154:157], v[198:201], v[44:47]
	v_mfma_f32_16x16x32_bf16 v[36:39], v[162:165], v[198:201], v[36:39]
	v_mfma_f32_16x16x32_bf16 v[28:31], v[154:157], v[206:209], v[28:31]
	v_mfma_f32_16x16x32_bf16 v[20:23], v[162:165], v[206:209], v[20:23]
	v_mfma_f32_16x16x32_bf16 v[12:15], v[154:157], v[214:217], v[12:15]
	v_mfma_f32_16x16x32_bf16 v[4:7], v[162:165], v[214:217], v[4:7]
	v_mfma_f32_16x16x32_bf16 v[56:59], v[166:169], v[182:185], v[56:59]
	v_mfma_f32_16x16x32_bf16 v[48:51], v[174:177], v[182:185], v[48:51]
	v_mfma_f32_16x16x32_bf16 v[40:43], v[166:169], v[194:197], v[40:43]
	v_mfma_f32_16x16x32_bf16 v[32:35], v[174:177], v[194:197], v[32:35]
	v_mfma_f32_16x16x32_bf16 v[24:27], v[166:169], v[202:205], v[24:27]
	v_mfma_f32_16x16x32_bf16 v[16:19], v[174:177], v[202:205], v[16:19]
	v_mfma_f32_16x16x32_bf16 v[8:11], v[166:169], v[210:213], v[8:11]
	v_mfma_f32_16x16x32_bf16 v[0:3], v[174:177], v[210:213], v[0:3]
	v_mfma_f32_16x16x32_bf16 v[56:59], v[170:173], v[186:189], v[56:59]
	v_mfma_f32_16x16x32_bf16 v[48:51], v[178:181], v[186:189], v[48:51]
	v_mfma_f32_16x16x32_bf16 v[40:43], v[170:173], v[198:201], v[40:43]
	v_mfma_f32_16x16x32_bf16 v[32:35], v[178:181], v[198:201], v[32:35]
	v_mfma_f32_16x16x32_bf16 v[24:27], v[170:173], v[206:209], v[24:27]
	v_mfma_f32_16x16x32_bf16 v[16:19], v[178:181], v[206:209], v[16:19]
	v_mfma_f32_16x16x32_bf16 v[8:11], v[170:173], v[214:217], v[8:11]
	v_mfma_f32_16x16x32_bf16 v[0:3], v[178:181], v[214:217], v[0:3]
	s_setprio 0
	s_barrier
	s_add_i32 s63, s63, 2
	s_add_u32 s44, s44, 0x100
	s_addc_u32 s45, s45, 0
	s_add_u32 s61, s61, 0x100
	s_addc_u32 s62, s62, 0
	s_cmp_gt_u32 s63, 13
	s_cbranch_scc0 .LBB0_577
	s_and_b64 vcc, exec, s[24:25]
	s_cbranch_vccz .LBB0_580
	s_barrier
